# K-loop: waits merged into one s_waitcnt behind setprio 1; M0 write moved ahead of the address add (s_nop removed) before each LDS-DMA
# speedup vs baseline: 1.0016x; 1.0016x over previous
; #define PG8_STAGE(bufoff, gbase, voff) do { _Pragma("unroll") for (int _i = 0; _i < 2; ++_i) \
;         __builtin_amdgcn_global_load_lds((const unsigned*)((const char*)(gbase) + (voff)[_i]), (LAS unsigned*)(lds + (bufoff) + ldsw + _i * 8192), 16, 0, 0); } while (0)
; #define PG8_LDA(dst, b, h) do { _Pragma("unroll") for (int m = 0; m < 4; ++m) _Pragma("unroll") for (int k = 0; k < 2; ++k) dst[m][k] = *(const LAS bf16x8*)(lds + PG8_SA(b, h) + aoff + m * 2048 + k * 1024); } while (0)
; #define PG8_LDB(dst, b, h) do { _Pragma("unroll") for (int n = 0; n < 2; ++n) _Pragma("unroll") for (int k = 0; k < 2; ++k) dst[n][k] = *(const LAS bf16x8*)(lds + PG8_SB(b, h) + boff + n * 2048 + k * 1024); } while (0)
; #define PG8_MMA(ai, bj, At, Bt) do { __builtin_amdgcn_s_setprio(1); _Pragma("unroll") for (int m = 0; m < 4; ++m) _Pragma("unroll") for (int n = 0; n < 2; ++n) _Pragma("unroll") for (int k = 0; k < 2; ++k) \
;         acc[ai][bj][m][n] = __builtin_amdgcn_mfma_f32_16x16x32_bf16(Bt[n][k], At[m][k], acc[ai][bj][m][n], 0, 0, 0); __builtin_amdgcn_s_setprio(0); } while (0)
; #define PG8_WAIT_V(n) asm volatile("s_waitcnt vmcnt(" #n ")" ::: "memory")
; #define PG8_WAIT_L(n) asm volatile("s_waitcnt lgkmcnt(" #n ")" ::: "memory")
; #define PG8_BAR __builtin_amdgcn_s_barrier()
; template <class Epi, int AMODE>
; __device__ __forceinline__ void gemm_phase(LAS unsigned char* lds, const Gemm g, const StaticOrder& S, const Epi& E, int stagger_us, int tid_in) {
;     ...
;         const char* nA = has_next ? Abase + (size_t)nxt.pm * tstepA : cA; const char* nB = has_next ? (const char*)g.Bt + (size_t)nxt.pn * tstepB : cB;
;         for (int t = 0; t < nt; t += 2) {
;             const bool last = (t == nt - 2);
;             const char* a1 = cA + (size_t)(t + 1) * kstep;
;             const char* a2 = last ? nA : cA + (size_t)(t + 2) * kstep; const char* b2 = last ? nB : cB + (size_t)(t + 2) * kstep;
;             const char* a3 = a2 + kstep; const char* b3 = b2 + kstep;
;             PG8_LDB(B0, 0, 0); PG8_LDB(B1, 0, 1); PG8_SCHED; PG8_LDA(At, 0, 0); PG8_STAGE(PG8_SA(1, 1), a1 + hstepA, voffA);
;             PG8_WAIT_V(8); PG8_WAIT_L(0); PG8_BAR; PG8_MMA(0, 0, At, B0); PG8_MMA(0, 1, At, B1); PG8_BAR; PG8_SCHED;
;             PG8_LDA(At, 0, 1); PG8_STAGE(PG8_SB(0, 0), b2, voffB); PG8_STAGE(PG8_SB(0, 1), b2 + hstepB, voffB); PG8_STAGE(PG8_SA(0, 0), a2, voffA);
.LBB0_396:
	s_add_u32 s4, s60, 0xfff80080
	s_addc_u32 s5, s61, -1
	s_add_i32 s30, 0, 0x10000
	s_cmp_eq_u32 s29, 28
	s_cselect_b32 s7, s27, s5
	s_cselect_b32 s6, s28, s4
	v_add_u32_e32 v140, s30, v162
	s_cselect_b32 s5, s49, vcc_hi
	s_cselect_b32 s4, s51, vcc_lo
	s_add_i32 s44, 0, 0x14000
	ds_read_b128 v[144:147], v140
	ds_read_b128 v[148:151], v140 offset:1024
	ds_read_b128 v[152:155], v140 offset:2048
	ds_read_b128 v[156:159], v140 offset:3072
	v_add_u32_e32 v140, s44, v162
	ds_read_b128 v[166:169], v140
	ds_read_b128 v[170:173], v140 offset:1024
	ds_read_b128 v[174:177], v140 offset:2048
	ds_read_b128 v[178:181], v140 offset:3072
	v_lshl_add_u64 v[140:141], s[60:61], 0, v[136:137]
	s_add_i32 m0, s57, 0xc000
	ds_read_b128 v[182:185], v164
	ds_read_b128 v[186:189], v164 offset:1024
	ds_read_b128 v[190:193], v164 offset:2048
	ds_read_b128 v[194:197], v164 offset:3072
	ds_read_b128 v[198:201], v164 offset:4096
	ds_read_b128 v[202:205], v164 offset:5120
	ds_read_b128 v[206:209], v164 offset:6144
	ds_read_b128 v[210:213], v164 offset:7168
	global_load_lds_dwordx4 v[140:141], off
	s_add_i32 m0, s57, 0xe000
	v_lshl_add_u64 v[140:141], s[60:61], 0, v[138:139]
	global_load_lds_dwordx4 v[140:141], off
	s_setprio 1
	s_waitcnt vmcnt(8) lgkmcnt(0)
	s_barrier
	v_mfma_f32_16x16x32_bf16 v[126:129], v[144:147], v[182:185], v[126:129]
	v_mfma_f32_16x16x32_bf16 v[122:125], v[152:155], v[182:185], v[122:125]
	v_mfma_f32_16x16x32_bf16 v[110:113], v[144:147], v[190:193], v[110:113]
	v_mfma_f32_16x16x32_bf16 v[106:109], v[152:155], v[190:193], v[106:109]
	v_mfma_f32_16x16x32_bf16 v[94:97], v[144:147], v[198:201], v[94:97]
	v_mfma_f32_16x16x32_bf16 v[90:93], v[152:155], v[198:201], v[90:93]
	v_mfma_f32_16x16x32_bf16 v[78:81], v[144:147], v[206:209], v[78:81]
	v_mfma_f32_16x16x32_bf16 v[74:77], v[152:155], v[206:209], v[74:77]
	v_mfma_f32_16x16x32_bf16 v[126:129], v[148:151], v[186:189], v[126:129]
	v_mfma_f32_16x16x32_bf16 v[122:125], v[156:159], v[186:189], v[122:125]
	v_mfma_f32_16x16x32_bf16 v[110:113], v[148:151], v[194:197], v[110:113]
	v_mfma_f32_16x16x32_bf16 v[106:109], v[156:159], v[194:197], v[106:109]
	v_mfma_f32_16x16x32_bf16 v[94:97], v[148:151], v[202:205], v[94:97]
	v_mfma_f32_16x16x32_bf16 v[90:93], v[156:159], v[202:205], v[90:93]
	v_mfma_f32_16x16x32_bf16 v[78:81], v[148:151], v[210:213], v[78:81]
	v_mfma_f32_16x16x32_bf16 v[74:77], v[156:159], v[210:213], v[74:77]
	v_mfma_f32_16x16x32_bf16 v[118:121], v[166:169], v[182:185], v[118:121]
	v_mfma_f32_16x16x32_bf16 v[114:117], v[174:177], v[182:185], v[114:117]
	v_mfma_f32_16x16x32_bf16 v[102:105], v[166:169], v[190:193], v[102:105]
	v_mfma_f32_16x16x32_bf16 v[98:101], v[174:177], v[190:193], v[98:101]
	v_mfma_f32_16x16x32_bf16 v[86:89], v[166:169], v[198:201], v[86:89]
	v_mfma_f32_16x16x32_bf16 v[82:85], v[174:177], v[198:201], v[82:85]
	v_mfma_f32_16x16x32_bf16 v[70:73], v[166:169], v[206:209], v[70:73]
	v_mfma_f32_16x16x32_bf16 v[66:69], v[174:177], v[206:209], v[66:69]
	v_mfma_f32_16x16x32_bf16 v[118:121], v[170:173], v[186:189], v[118:121]
	v_mfma_f32_16x16x32_bf16 v[114:117], v[178:181], v[186:189], v[114:117]
	v_mfma_f32_16x16x32_bf16 v[102:105], v[170:173], v[194:197], v[102:105]
	v_mfma_f32_16x16x32_bf16 v[98:101], v[178:181], v[194:197], v[98:101]
	v_mfma_f32_16x16x32_bf16 v[86:89], v[170:173], v[202:205], v[86:89]
	v_mfma_f32_16x16x32_bf16 v[82:85], v[178:181], v[202:205], v[82:85]
	v_mfma_f32_16x16x32_bf16 v[70:73], v[170:173], v[210:213], v[70:73]
	v_mfma_f32_16x16x32_bf16 v[66:69], v[178:181], v[210:213], v[66:69]
	s_setprio 0
	s_barrier
	s_add_i32 s30, s30, s66
	v_lshl_add_u64 v[140:141], s[4:5], 0, v[0:1]
	s_mov_b32 m0, s30
	ds_read_b128 v[182:185], v164 offset:16384
	ds_read_b128 v[186:189], v164 offset:17408
	ds_read_b128 v[190:193], v164 offset:18432
	ds_read_b128 v[194:197], v164 offset:19456
	ds_read_b128 v[198:201], v164 offset:20480
	ds_read_b128 v[202:205], v164 offset:21504
	ds_read_b128 v[206:209], v164 offset:22528
	ds_read_b128 v[210:213], v164 offset:23552
	global_load_lds_dwordx4 v[140:141], off
	s_add_i32 m0, s30, 0x2000
	s_add_u32 s30, s4, 0x80000
	v_lshl_add_u64 v[160:161], s[4:5], 0, v[130:131]
	s_addc_u32 s31, s5, 0
	s_add_i32 s44, s44, s66
	global_load_lds_dwordx4 v[160:161], off
	v_lshl_add_u64 v[214:215], s[30:31], 0, v[0:1]
	s_mov_b32 m0, s44
	v_lshl_add_u64 v[216:217], s[6:7], 0, v[132:133]
	global_load_lds_dwordx4 v[214:215], off
	s_add_i32 m0, s44, 0x2000
	v_lshl_add_u64 v[214:215], s[30:31], 0, v[130:131]
	global_load_lds_dwordx4 v[214:215], off
	s_mov_b32 m0, s57
	v_lshl_add_u64 v[214:215], s[6:7], 0, v[134:135]
	global_load_lds_dwordx4 v[214:215], off
	s_mov_b32 m0, s59
	s_nop 0
	global_load_lds_dwordx4 v[216:217], off
	s_setprio 1
	s_waitcnt vmcnt(8) lgkmcnt(0)
	s_barrier
; #define PG8_STAGE(bufoff, gbase, voff) do { _Pragma("unroll") for (int _i = 0; _i < 2; ++_i) \
;         __builtin_amdgcn_global_load_lds((const unsigned*)((const char*)(gbase) + (voff)[_i]), (LAS unsigned*)(lds + (bufoff) + ldsw + _i * 8192), 16, 0, 0); } while (0)
; #define PG8_LDA(dst, b, h) do { _Pragma("unroll") for (int m = 0; m < 4; ++m) _Pragma("unroll") for (int k = 0; k < 2; ++k) dst[m][k] = *(const LAS bf16x8*)(lds + PG8_SA(b, h) + aoff + m * 2048 + k * 1024); } while (0)
; #define PG8_LDB(dst, b, h) do { _Pragma("unroll") for (int n = 0; n < 2; ++n) _Pragma("unroll") for (int k = 0; k < 2; ++k) dst[n][k] = *(const LAS bf16x8*)(lds + PG8_SB(b, h) + boff + n * 2048 + k * 1024); } while (0)
; #define PG8_MMA(ai, bj, At, Bt) do { __builtin_amdgcn_s_setprio(1); _Pragma("unroll") for (int m = 0; m < 4; ++m) _Pragma("unroll") for (int n = 0; n < 2; ++n) _Pragma("unroll") for (int k = 0; k < 2; ++k) \
;         acc[ai][bj][m][n] = __builtin_amdgcn_mfma_f32_16x16x32_bf16(Bt[n][k], At[m][k], acc[ai][bj][m][n], 0, 0, 0); __builtin_amdgcn_s_setprio(0); } while (0)
; #define PG8_WAIT_V(n) asm volatile("s_waitcnt vmcnt(" #n ")" ::: "memory")
; #define PG8_WAIT_L(n) asm volatile("s_waitcnt lgkmcnt(" #n ")" ::: "memory")
; #define PG8_BAR __builtin_amdgcn_s_barrier()
; #define PG8_SCHED __builtin_amdgcn_sched_barrier(0)
; template <class Epi, int AMODE>
; __device__ __forceinline__ void gemm_phase(LAS unsigned char* lds, const Gemm g, const StaticOrder& S, const Epi& E, int stagger_us, int tid_in) {
;     ...
;             PG8_WAIT_V(8); PG8_WAIT_L(0); PG8_BAR; PG8_MMA(1, 0, At, B0); PG8_MMA(1, 1, At, B1); PG8_BAR; PG8_SCHED;
;             PG8_LDB(B0, 1, 0); PG8_LDB(B1, 1, 1); PG8_SCHED; PG8_LDA(At, 1, 0); PG8_STAGE(PG8_SA(0, 1), a2 + hstepA, voffA);
;             PG8_WAIT_V(8); PG8_WAIT_L(0); PG8_BAR; PG8_MMA(0, 0, At, B0); PG8_MMA(0, 1, At, B1); PG8_BAR; PG8_SCHED;
	v_mfma_f32_16x16x32_bf16 v[62:65], v[144:147], v[182:185], v[62:65]
	v_mfma_f32_16x16x32_bf16 v[58:61], v[152:155], v[182:185], v[58:61]
	v_mfma_f32_16x16x32_bf16 v[46:49], v[144:147], v[190:193], v[46:49]
	v_mfma_f32_16x16x32_bf16 v[42:45], v[152:155], v[190:193], v[42:45]
	v_mfma_f32_16x16x32_bf16 v[30:33], v[144:147], v[198:201], v[30:33]
	v_mfma_f32_16x16x32_bf16 v[26:29], v[152:155], v[198:201], v[26:29]
	v_mfma_f32_16x16x32_bf16 v[14:17], v[144:147], v[206:209], v[14:17]
	v_mfma_f32_16x16x32_bf16 v[10:13], v[152:155], v[206:209], v[10:13]
	v_mfma_f32_16x16x32_bf16 v[62:65], v[148:151], v[186:189], v[62:65]
	v_mfma_f32_16x16x32_bf16 v[58:61], v[156:159], v[186:189], v[58:61]
	v_mfma_f32_16x16x32_bf16 v[46:49], v[148:151], v[194:197], v[46:49]
	v_mfma_f32_16x16x32_bf16 v[42:45], v[156:159], v[194:197], v[42:45]
	v_mfma_f32_16x16x32_bf16 v[30:33], v[148:151], v[202:205], v[30:33]
	v_mfma_f32_16x16x32_bf16 v[26:29], v[156:159], v[202:205], v[26:29]
	v_mfma_f32_16x16x32_bf16 v[14:17], v[148:151], v[210:213], v[14:17]
	v_mfma_f32_16x16x32_bf16 v[10:13], v[156:159], v[210:213], v[10:13]
	v_mfma_f32_16x16x32_bf16 v[54:57], v[166:169], v[182:185], v[54:57]
	v_mfma_f32_16x16x32_bf16 v[50:53], v[174:177], v[182:185], v[50:53]
	v_mfma_f32_16x16x32_bf16 v[38:41], v[166:169], v[190:193], v[38:41]
	v_mfma_f32_16x16x32_bf16 v[34:37], v[174:177], v[190:193], v[34:37]
	v_mfma_f32_16x16x32_bf16 v[22:25], v[166:169], v[198:201], v[22:25]
	v_mfma_f32_16x16x32_bf16 v[18:21], v[174:177], v[198:201], v[18:21]
	v_mfma_f32_16x16x32_bf16 v[6:9], v[166:169], v[206:209], v[6:9]
	v_mfma_f32_16x16x32_bf16 v[2:5], v[174:177], v[206:209], v[2:5]
	v_mfma_f32_16x16x32_bf16 v[54:57], v[170:173], v[186:189], v[54:57]
	v_mfma_f32_16x16x32_bf16 v[50:53], v[178:181], v[186:189], v[50:53]
	v_mfma_f32_16x16x32_bf16 v[38:41], v[170:173], v[194:197], v[38:41]
	v_mfma_f32_16x16x32_bf16 v[34:37], v[178:181], v[194:197], v[34:37]
	v_mfma_f32_16x16x32_bf16 v[22:25], v[170:173], v[202:205], v[22:25]
	v_mfma_f32_16x16x32_bf16 v[18:21], v[178:181], v[202:205], v[18:21]
	v_mfma_f32_16x16x32_bf16 v[6:9], v[170:173], v[210:213], v[6:9]
	v_mfma_f32_16x16x32_bf16 v[2:5], v[178:181], v[210:213], v[2:5]
	s_setprio 0
	s_barrier
	s_add_i32 s30, 0, 0x18000
	v_add_u32_e32 v142, s30, v162
	s_add_i32 s31, 0, 0x1c000
	ds_read_b128 v[144:147], v142
	ds_read_b128 v[148:151], v142 offset:1024
	ds_read_b128 v[152:155], v142 offset:2048
	ds_read_b128 v[156:159], v142 offset:3072
	v_add_u32_e32 v142, s31, v162
	ds_read_b128 v[166:169], v142
	ds_read_b128 v[170:173], v142 offset:1024
	ds_read_b128 v[174:177], v142 offset:2048
	ds_read_b128 v[178:181], v142 offset:3072
	s_add_u32 s6, s6, 0x80000
	s_addc_u32 s7, s7, 0
	s_mov_b32 m0, s87
	v_lshl_add_u64 v[218:219], s[6:7], 0, v[134:135]
	ds_read_b128 v[182:185], v164 offset:32768
	ds_read_b128 v[186:189], v164 offset:33792
	ds_read_b128 v[190:193], v164 offset:34816
	ds_read_b128 v[194:197], v164 offset:35840
	ds_read_b128 v[198:201], v164 offset:36864
	ds_read_b128 v[202:205], v164 offset:37888
	ds_read_b128 v[206:209], v164 offset:38912
	ds_read_b128 v[210:213], v164 offset:39936
	global_load_lds_dwordx4 v[218:219], off
	s_mov_b32 m0, s91
	v_lshl_add_u64 v[218:219], s[6:7], 0, v[132:133]
	global_load_lds_dwordx4 v[218:219], off
	s_setprio 1
	s_waitcnt vmcnt(8) lgkmcnt(0)
	s_barrier
	v_mfma_f32_16x16x32_bf16 v[126:129], v[144:147], v[182:185], v[126:129]
	v_mfma_f32_16x16x32_bf16 v[122:125], v[152:155], v[182:185], v[122:125]
	v_mfma_f32_16x16x32_bf16 v[110:113], v[144:147], v[190:193], v[110:113]
	v_mfma_f32_16x16x32_bf16 v[106:109], v[152:155], v[190:193], v[106:109]
	v_mfma_f32_16x16x32_bf16 v[94:97], v[144:147], v[198:201], v[94:97]
	v_mfma_f32_16x16x32_bf16 v[90:93], v[152:155], v[198:201], v[90:93]
	v_mfma_f32_16x16x32_bf16 v[78:81], v[144:147], v[206:209], v[78:81]
	v_mfma_f32_16x16x32_bf16 v[74:77], v[152:155], v[206:209], v[74:77]
	v_mfma_f32_16x16x32_bf16 v[126:129], v[148:151], v[186:189], v[126:129]
	v_mfma_f32_16x16x32_bf16 v[122:125], v[156:159], v[186:189], v[122:125]
	v_mfma_f32_16x16x32_bf16 v[110:113], v[148:151], v[194:197], v[110:113]
	v_mfma_f32_16x16x32_bf16 v[106:109], v[156:159], v[194:197], v[106:109]
	v_mfma_f32_16x16x32_bf16 v[94:97], v[148:151], v[202:205], v[94:97]
	v_mfma_f32_16x16x32_bf16 v[90:93], v[156:159], v[202:205], v[90:93]
	v_mfma_f32_16x16x32_bf16 v[78:81], v[148:151], v[210:213], v[78:81]
	v_mfma_f32_16x16x32_bf16 v[74:77], v[156:159], v[210:213], v[74:77]
	v_mfma_f32_16x16x32_bf16 v[118:121], v[166:169], v[182:185], v[118:121]
	v_mfma_f32_16x16x32_bf16 v[114:117], v[174:177], v[182:185], v[114:117]
	v_mfma_f32_16x16x32_bf16 v[102:105], v[166:169], v[190:193], v[102:105]
	v_mfma_f32_16x16x32_bf16 v[98:101], v[174:177], v[190:193], v[98:101]
	v_mfma_f32_16x16x32_bf16 v[86:89], v[166:169], v[198:201], v[86:89]
	v_mfma_f32_16x16x32_bf16 v[82:85], v[174:177], v[198:201], v[82:85]
	v_mfma_f32_16x16x32_bf16 v[70:73], v[166:169], v[206:209], v[70:73]
	v_mfma_f32_16x16x32_bf16 v[66:69], v[174:177], v[206:209], v[66:69]
	v_mfma_f32_16x16x32_bf16 v[118:121], v[170:173], v[186:189], v[118:121]
	v_mfma_f32_16x16x32_bf16 v[114:117], v[178:181], v[186:189], v[114:117]
	v_mfma_f32_16x16x32_bf16 v[102:105], v[170:173], v[194:197], v[102:105]
	v_mfma_f32_16x16x32_bf16 v[98:101], v[178:181], v[194:197], v[98:101]
	v_mfma_f32_16x16x32_bf16 v[86:89], v[170:173], v[202:205], v[86:89]
	v_mfma_f32_16x16x32_bf16 v[82:85], v[178:181], v[202:205], v[82:85]
	v_mfma_f32_16x16x32_bf16 v[70:73], v[170:173], v[210:213], v[70:73]
	v_mfma_f32_16x16x32_bf16 v[66:69], v[178:181], v[210:213], v[66:69]
	s_setprio 0
	s_barrier
; #define PG8_STAGE(bufoff, gbase, voff) do { _Pragma("unroll") for (int _i = 0; _i < 2; ++_i) \
;         __builtin_amdgcn_global_load_lds((const unsigned*)((const char*)(gbase) + (voff)[_i]), (LAS unsigned*)(lds + (bufoff) + ldsw + _i * 8192), 16, 0, 0); } while (0)
; #define PG8_LDA(dst, b, h) do { _Pragma("unroll") for (int m = 0; m < 4; ++m) _Pragma("unroll") for (int k = 0; k < 2; ++k) dst[m][k] = *(const LAS bf16x8*)(lds + PG8_SA(b, h) + aoff + m * 2048 + k * 1024); } while (0)
; #define PG8_MMA(ai, bj, At, Bt) do { __builtin_amdgcn_s_setprio(1); _Pragma("unroll") for (int m = 0; m < 4; ++m) _Pragma("unroll") for (int n = 0; n < 2; ++n) _Pragma("unroll") for (int k = 0; k < 2; ++k) \
;         acc[ai][bj][m][n] = __builtin_amdgcn_mfma_f32_16x16x32_bf16(Bt[n][k], At[m][k], acc[ai][bj][m][n], 0, 0, 0); __builtin_amdgcn_s_setprio(0); } while (0)
; #define PG8_WAIT_V(n) asm volatile("s_waitcnt vmcnt(" #n ")" ::: "memory")
; #define PG8_WAIT_L(n) asm volatile("s_waitcnt lgkmcnt(" #n ")" ::: "memory")
; #define PG8_BAR __builtin_amdgcn_s_barrier()
; #define PG8_SCHED __builtin_amdgcn_sched_barrier(0)
; template <class Epi, int AMODE>
; __device__ __forceinline__ void gemm_phase(LAS unsigned char* lds, const Gemm g, const StaticOrder& S, const Epi& E, int stagger_us, int tid_in) {
;     ...
;             PG8_LDA(At, 1, 1); PG8_STAGE(PG8_SB(1, 0), b3, voffB); PG8_STAGE(PG8_SB(1, 1), b3 + hstepB, voffB); PG8_STAGE(PG8_SA(1, 0), a3, voffA);
;             PG8_WAIT_V(8); PG8_WAIT_L(0); PG8_BAR; PG8_MMA(1, 0, At, B0); PG8_MMA(1, 1, At, B1); PG8_BAR; PG8_SCHED;
	s_add_i32 s6, s30, s66
	v_lshl_add_u64 v[140:141], v[140:141], 0, s[74:75]
	s_mov_b32 m0, s6
	ds_read_b128 v[182:185], v164 offset:49152
	ds_read_b128 v[186:189], v164 offset:50176
	ds_read_b128 v[190:193], v164 offset:51200
	ds_read_b128 v[194:197], v164 offset:52224
	ds_read_b128 v[198:201], v164 offset:53248
	ds_read_b128 v[202:205], v164 offset:54272
	ds_read_b128 v[206:209], v164 offset:55296
	ds_read_b128 v[210:213], v164 offset:56320
	global_load_lds_dwordx4 v[140:141], off
	s_add_i32 m0, s6, 0x2000
	s_add_u32 s4, s4, 0x80080
	v_lshl_add_u64 v[140:141], v[160:161], 0, s[74:75]
	s_addc_u32 s5, s5, 0
	s_add_i32 s6, s31, s66
	global_load_lds_dwordx4 v[140:141], off
	s_mov_b32 m0, s6
	v_lshl_add_u64 v[140:141], s[4:5], 0, v[0:1]
	global_load_lds_dwordx4 v[140:141], off
	s_add_i32 m0, s6, 0x2000
	v_lshl_add_u64 v[140:141], s[4:5], 0, v[130:131]
	global_load_lds_dwordx4 v[140:141], off
	s_mov_b32 m0, s95
	v_lshl_add_u64 v[140:141], v[214:215], 0, s[74:75]
	global_load_lds_dwordx4 v[140:141], off
	s_mov_b32 m0, s96
	v_lshl_add_u64 v[140:141], v[216:217], 0, s[74:75]
	global_load_lds_dwordx4 v[140:141], off
	s_setprio 1
	s_waitcnt vmcnt(8) lgkmcnt(0)
	s_barrier
	v_mfma_f32_16x16x32_bf16 v[62:65], v[144:147], v[182:185], v[62:65]
	v_mfma_f32_16x16x32_bf16 v[58:61], v[152:155], v[182:185], v[58:61]
	v_mfma_f32_16x16x32_bf16 v[46:49], v[144:147], v[190:193], v[46:49]
	v_mfma_f32_16x16x32_bf16 v[42:45], v[152:155], v[190:193], v[42:45]
	v_mfma_f32_16x16x32_bf16 v[30:33], v[144:147], v[198:201], v[30:33]
	v_mfma_f32_16x16x32_bf16 v[26:29], v[152:155], v[198:201], v[26:29]
	v_mfma_f32_16x16x32_bf16 v[14:17], v[144:147], v[206:209], v[14:17]
	v_mfma_f32_16x16x32_bf16 v[10:13], v[152:155], v[206:209], v[10:13]
	v_mfma_f32_16x16x32_bf16 v[62:65], v[148:151], v[186:189], v[62:65]
	v_mfma_f32_16x16x32_bf16 v[58:61], v[156:159], v[186:189], v[58:61]
	v_mfma_f32_16x16x32_bf16 v[46:49], v[148:151], v[194:197], v[46:49]
	v_mfma_f32_16x16x32_bf16 v[42:45], v[156:159], v[194:197], v[42:45]
	v_mfma_f32_16x16x32_bf16 v[30:33], v[148:151], v[202:205], v[30:33]
	v_mfma_f32_16x16x32_bf16 v[26:29], v[156:159], v[202:205], v[26:29]
	v_mfma_f32_16x16x32_bf16 v[14:17], v[148:151], v[210:213], v[14:17]
	v_mfma_f32_16x16x32_bf16 v[10:13], v[156:159], v[210:213], v[10:13]
	v_mfma_f32_16x16x32_bf16 v[54:57], v[166:169], v[182:185], v[54:57]
	v_mfma_f32_16x16x32_bf16 v[50:53], v[174:177], v[182:185], v[50:53]
	v_mfma_f32_16x16x32_bf16 v[38:41], v[166:169], v[190:193], v[38:41]
	v_mfma_f32_16x16x32_bf16 v[34:37], v[174:177], v[190:193], v[34:37]
	v_mfma_f32_16x16x32_bf16 v[22:25], v[166:169], v[198:201], v[22:25]
	v_mfma_f32_16x16x32_bf16 v[18:21], v[174:177], v[198:201], v[18:21]
	v_mfma_f32_16x16x32_bf16 v[6:9], v[166:169], v[206:209], v[6:9]
	v_mfma_f32_16x16x32_bf16 v[2:5], v[174:177], v[206:209], v[2:5]
	v_mfma_f32_16x16x32_bf16 v[54:57], v[170:173], v[186:189], v[54:57]
	v_mfma_f32_16x16x32_bf16 v[50:53], v[178:181], v[186:189], v[50:53]
	v_mfma_f32_16x16x32_bf16 v[38:41], v[170:173], v[194:197], v[38:41]
	v_mfma_f32_16x16x32_bf16 v[34:37], v[178:181], v[194:197], v[34:37]
	v_mfma_f32_16x16x32_bf16 v[22:25], v[170:173], v[202:205], v[22:25]
	v_mfma_f32_16x16x32_bf16 v[18:21], v[178:181], v[202:205], v[18:21]
	v_mfma_f32_16x16x32_bf16 v[6:9], v[170:173], v[210:213], v[6:9]
	v_mfma_f32_16x16x32_bf16 v[2:5], v[178:181], v[210:213], v[2:5]
	s_setprio 0
	s_barrier
	s_add_i32 s29, s29, 2
	s_add_u32 s60, s60, 0x100
	s_addc_u32 s61, s61, 0
	s_add_u32 vcc_lo, vcc_lo, 0x100
	s_addc_u32 vcc_hi, vcc_hi, 0
	s_cmp_gt_u32 s29, 29
	s_cbranch_scc0 .LBB0_396
	s_and_b64 vcc, exec, s[46:47]
	s_cbranch_vccz .LBB0_399
	s_barrier

; #define PG8_STAGE(bufoff, gbase, voff) do { _Pragma("unroll") for (int _i = 0; _i < 2; ++_i) \
;         __builtin_amdgcn_global_load_lds((const unsigned*)((const char*)(gbase) + (voff)[_i]), (LAS unsigned*)(lds + (bufoff) + ldsw + _i * 8192), 16, 0, 0); } while (0)
; #define PG8_LDA(dst, b, h) do { _Pragma("unroll") for (int m = 0; m < 4; ++m) _Pragma("unroll") for (int k = 0; k < 2; ++k) dst[m][k] = *(const LAS bf16x8*)(lds + PG8_SA(b, h) + aoff + m * 2048 + k * 1024); } while (0)
; #define PG8_LDB(dst, b, h) do { _Pragma("unroll") for (int n = 0; n < 2; ++n) _Pragma("unroll") for (int k = 0; k < 2; ++k) dst[n][k] = *(const LAS bf16x8*)(lds + PG8_SB(b, h) + boff + n * 2048 + k * 1024); } while (0)
; #define PG8_MMA(ai, bj, At, Bt) do { __builtin_amdgcn_s_setprio(1); _Pragma("unroll") for (int m = 0; m < 4; ++m) _Pragma("unroll") for (int n = 0; n < 2; ++n) _Pragma("unroll") for (int k = 0; k < 2; ++k) \
;         acc[ai][bj][m][n] = __builtin_amdgcn_mfma_f32_16x16x32_bf16(Bt[n][k], At[m][k], acc[ai][bj][m][n], 0, 0, 0); __builtin_amdgcn_s_setprio(0); } while (0)
; #define PG8_WAIT_V(n) asm volatile("s_waitcnt vmcnt(" #n ")" ::: "memory")
; #define PG8_WAIT_L(n) asm volatile("s_waitcnt lgkmcnt(" #n ")" ::: "memory")
; #define PG8_BAR __builtin_amdgcn_s_barrier()
; template <class Epi, int AMODE>
; __device__ __forceinline__ void gemm_phase(LAS unsigned char* lds, const Gemm g, const StaticOrder& S, const Epi& E, int stagger_us, int tid_in) {
;     ...
;         const char* nA = has_next ? Abase + (size_t)nxt.pm * tstepA : cA; const char* nB = has_next ? (const char*)g.Bt + (size_t)nxt.pn * tstepB : cB;
;         for (int t = 0; t < nt; t += 2) {
;             const bool last = (t == nt - 2);
;             const char* a1 = cA + (size_t)(t + 1) * kstep;
;             const char* a2 = last ? nA : cA + (size_t)(t + 2) * kstep; const char* b2 = last ? nB : cB + (size_t)(t + 2) * kstep;
;             const char* a3 = a2 + kstep; const char* b3 = b2 + kstep;
;             PG8_LDB(B0, 0, 0); PG8_LDB(B1, 0, 1); PG8_SCHED; PG8_LDA(At, 0, 0); PG8_STAGE(PG8_SA(1, 1), a1 + hstepA, voffA);
;             PG8_WAIT_V(8); PG8_WAIT_L(0); PG8_BAR; PG8_MMA(0, 0, At, B0); PG8_MMA(0, 1, At, B1); PG8_BAR; PG8_SCHED;
;             PG8_LDA(At, 0, 1); PG8_STAGE(PG8_SB(0, 0), b2, voffB); PG8_STAGE(PG8_SB(0, 1), b2 + hstepB, voffB); PG8_STAGE(PG8_SA(0, 0), a2, voffA);
.LBB0_1199:
	s_add_u32 s4, s46, 0x100
	s_addc_u32 s5, s47, 0
	s_add_i32 s34, 0, 0x10000
	s_cmp_eq_u32 s31, 28
	s_cselect_b32 s95, s61, s5
	s_cselect_b32 s94, vcc_lo, s4
	s_cselect_b32 s7, s59, s30
	s_cselect_b32 s6, vcc_hi, s29
	s_add_i32 s35, 0, 0x14000
	v_add_u32_e32 v62, s34, v205
	v_add_u32_e32 v158, s35, v205
	ds_read_b128 v[50:53], v62
	ds_read_b128 v[54:57], v62 offset:1024
	ds_read_b128 v[58:61], v62 offset:2048
	ds_read_b128 v[62:65], v62 offset:3072
	ds_read_b128 v[146:149], v158
	ds_read_b128 v[150:153], v158 offset:1024
	ds_read_b128 v[154:157], v158 offset:2048
	ds_read_b128 v[158:161], v158 offset:3072
	v_lshl_add_u64 v[200:201], s[46:47], 0, v[176:177]
	s_add_i32 m0, s66, 0xc000
	ds_read_b128 v[162:165], v207
	ds_read_b128 v[166:169], v207 offset:1024
	ds_read_b128 v[170:173], v207 offset:2048
	ds_read_b128 v[180:183], v207 offset:3072
	ds_read_b128 v[184:187], v207 offset:4096
	ds_read_b128 v[188:191], v207 offset:5120
	ds_read_b128 v[192:195], v207 offset:6144
	ds_read_b128 v[196:199], v207 offset:7168
	global_load_lds_dwordx4 v[200:201], off
	s_add_i32 m0, s66, 0xe000
	v_lshl_add_u64 v[200:201], s[46:47], 0, v[178:179]
	global_load_lds_dwordx4 v[200:201], off
	s_setprio 1
	s_waitcnt vmcnt(8) lgkmcnt(0)
	s_barrier
	v_mfma_f32_16x16x32_bf16 v[142:145], v[50:53], v[162:165], v[142:145]
	v_mfma_f32_16x16x32_bf16 v[138:141], v[58:61], v[162:165], v[138:141]
	v_mfma_f32_16x16x32_bf16 v[126:129], v[50:53], v[170:173], v[126:129]
	v_mfma_f32_16x16x32_bf16 v[122:125], v[58:61], v[170:173], v[122:125]
	v_mfma_f32_16x16x32_bf16 v[110:113], v[50:53], v[184:187], v[110:113]
	v_mfma_f32_16x16x32_bf16 v[106:109], v[58:61], v[184:187], v[106:109]
	v_mfma_f32_16x16x32_bf16 v[94:97], v[50:53], v[192:195], v[94:97]
	v_mfma_f32_16x16x32_bf16 v[90:93], v[58:61], v[192:195], v[90:93]
	v_mfma_f32_16x16x32_bf16 v[142:145], v[54:57], v[166:169], v[142:145]
	v_mfma_f32_16x16x32_bf16 v[138:141], v[62:65], v[166:169], v[138:141]
	v_mfma_f32_16x16x32_bf16 v[126:129], v[54:57], v[180:183], v[126:129]
	v_mfma_f32_16x16x32_bf16 v[122:125], v[62:65], v[180:183], v[122:125]
	v_mfma_f32_16x16x32_bf16 v[110:113], v[54:57], v[188:191], v[110:113]
	v_mfma_f32_16x16x32_bf16 v[106:109], v[62:65], v[188:191], v[106:109]
	v_mfma_f32_16x16x32_bf16 v[94:97], v[54:57], v[196:199], v[94:97]
	v_mfma_f32_16x16x32_bf16 v[90:93], v[62:65], v[196:199], v[90:93]
	v_mfma_f32_16x16x32_bf16 v[134:137], v[146:149], v[162:165], v[134:137]
	v_mfma_f32_16x16x32_bf16 v[130:133], v[154:157], v[162:165], v[130:133]
	v_mfma_f32_16x16x32_bf16 v[118:121], v[146:149], v[170:173], v[118:121]
	v_mfma_f32_16x16x32_bf16 v[114:117], v[154:157], v[170:173], v[114:117]
	v_mfma_f32_16x16x32_bf16 v[102:105], v[146:149], v[184:187], v[102:105]
	v_mfma_f32_16x16x32_bf16 v[98:101], v[154:157], v[184:187], v[98:101]
	v_mfma_f32_16x16x32_bf16 v[86:89], v[146:149], v[192:195], v[86:89]
	v_mfma_f32_16x16x32_bf16 v[82:85], v[154:157], v[192:195], v[82:85]
	v_mfma_f32_16x16x32_bf16 v[134:137], v[150:153], v[166:169], v[134:137]
	v_mfma_f32_16x16x32_bf16 v[130:133], v[158:161], v[166:169], v[130:133]
	v_mfma_f32_16x16x32_bf16 v[118:121], v[150:153], v[180:183], v[118:121]
	v_mfma_f32_16x16x32_bf16 v[114:117], v[158:161], v[180:183], v[114:117]
	v_mfma_f32_16x16x32_bf16 v[102:105], v[150:153], v[188:191], v[102:105]
	v_mfma_f32_16x16x32_bf16 v[98:101], v[158:161], v[188:191], v[98:101]
	v_mfma_f32_16x16x32_bf16 v[86:89], v[150:153], v[196:199], v[86:89]
	v_mfma_f32_16x16x32_bf16 v[82:85], v[158:161], v[196:199], v[82:85]
	s_setprio 0
	s_barrier
	s_add_i32 s34, s34, s13
	v_lshl_add_u64 v[200:201], s[6:7], 0, v[0:1]
	s_mov_b32 m0, s34
	ds_read_b128 v[162:165], v207 offset:16384
	ds_read_b128 v[166:169], v207 offset:17408
	ds_read_b128 v[170:173], v207 offset:18432
	ds_read_b128 v[180:183], v207 offset:19456
	ds_read_b128 v[184:187], v207 offset:20480
	ds_read_b128 v[188:191], v207 offset:21504
	ds_read_b128 v[192:195], v207 offset:22528
	ds_read_b128 v[196:199], v207 offset:23552
	global_load_lds_dwordx4 v[200:201], off
	s_add_i32 m0, s34, 0x2000
	s_add_u32 s46, s6, 0x80000
	v_lshl_add_u64 v[202:203], s[6:7], 0, v[174:175]
	s_addc_u32 s47, s7, 0
	s_add_i32 s34, s35, s13
	global_load_lds_dwordx4 v[202:203], off
	v_lshl_add_u64 v[208:209], s[46:47], 0, v[0:1]
	s_mov_b32 m0, s34
	v_lshl_add_u64 v[210:211], s[94:95], 0, v[174:175]
	global_load_lds_dwordx4 v[208:209], off
	s_add_i32 m0, s34, 0x2000
	v_lshl_add_u64 v[208:209], s[46:47], 0, v[174:175]
	global_load_lds_dwordx4 v[208:209], off
	s_mov_b32 m0, s66
	v_lshl_add_u64 v[208:209], s[94:95], 0, v[0:1]
	global_load_lds_dwordx4 v[208:209], off
	s_mov_b32 m0, s67
	s_nop 0
	global_load_lds_dwordx4 v[210:211], off
	s_setprio 1
	s_waitcnt vmcnt(8) lgkmcnt(0)
	s_barrier
; #define PG8_STAGE(bufoff, gbase, voff) do { _Pragma("unroll") for (int _i = 0; _i < 2; ++_i) \
;         __builtin_amdgcn_global_load_lds((const unsigned*)((const char*)(gbase) + (voff)[_i]), (LAS unsigned*)(lds + (bufoff) + ldsw + _i * 8192), 16, 0, 0); } while (0)
; #define PG8_LDA(dst, b, h) do { _Pragma("unroll") for (int m = 0; m < 4; ++m) _Pragma("unroll") for (int k = 0; k < 2; ++k) dst[m][k] = *(const LAS bf16x8*)(lds + PG8_SA(b, h) + aoff + m * 2048 + k * 1024); } while (0)
; #define PG8_LDB(dst, b, h) do { _Pragma("unroll") for (int n = 0; n < 2; ++n) _Pragma("unroll") for (int k = 0; k < 2; ++k) dst[n][k] = *(const LAS bf16x8*)(lds + PG8_SB(b, h) + boff + n * 2048 + k * 1024); } while (0)
; #define PG8_MMA(ai, bj, At, Bt) do { __builtin_amdgcn_s_setprio(1); _Pragma("unroll") for (int m = 0; m < 4; ++m) _Pragma("unroll") for (int n = 0; n < 2; ++n) _Pragma("unroll") for (int k = 0; k < 2; ++k) \
;         acc[ai][bj][m][n] = __builtin_amdgcn_mfma_f32_16x16x32_bf16(Bt[n][k], At[m][k], acc[ai][bj][m][n], 0, 0, 0); __builtin_amdgcn_s_setprio(0); } while (0)
; #define PG8_WAIT_V(n) asm volatile("s_waitcnt vmcnt(" #n ")" ::: "memory")
; #define PG8_WAIT_L(n) asm volatile("s_waitcnt lgkmcnt(" #n ")" ::: "memory")
; #define PG8_BAR __builtin_amdgcn_s_barrier()
; #define PG8_SCHED __builtin_amdgcn_sched_barrier(0)
; template <class Epi, int AMODE>
; __device__ __forceinline__ void gemm_phase(LAS unsigned char* lds, const Gemm g, const StaticOrder& S, const Epi& E, int stagger_us, int tid_in) {
;     ...
;             PG8_WAIT_V(8); PG8_WAIT_L(0); PG8_BAR; PG8_MMA(1, 0, At, B0); PG8_MMA(1, 1, At, B1); PG8_BAR; PG8_SCHED;
;             PG8_LDB(B0, 1, 0); PG8_LDB(B1, 1, 1); PG8_SCHED; PG8_LDA(At, 1, 0); PG8_STAGE(PG8_SA(0, 1), a2 + hstepA, voffA);
;             PG8_WAIT_V(8); PG8_WAIT_L(0); PG8_BAR; PG8_MMA(0, 0, At, B0); PG8_MMA(0, 1, At, B1); PG8_BAR; PG8_SCHED;
	v_mfma_f32_16x16x32_bf16 v[78:81], v[50:53], v[162:165], v[78:81]
	v_mfma_f32_16x16x32_bf16 v[74:77], v[58:61], v[162:165], v[74:77]
	v_mfma_f32_16x16x32_bf16 v[46:49], v[50:53], v[170:173], v[46:49]
	v_mfma_f32_16x16x32_bf16 v[42:45], v[58:61], v[170:173], v[42:45]
	v_mfma_f32_16x16x32_bf16 v[30:33], v[50:53], v[184:187], v[30:33]
	v_mfma_f32_16x16x32_bf16 v[26:29], v[58:61], v[184:187], v[26:29]
	v_mfma_f32_16x16x32_bf16 v[14:17], v[50:53], v[192:195], v[14:17]
	v_mfma_f32_16x16x32_bf16 v[10:13], v[58:61], v[192:195], v[10:13]
	v_mfma_f32_16x16x32_bf16 v[78:81], v[54:57], v[166:169], v[78:81]
	v_mfma_f32_16x16x32_bf16 v[74:77], v[62:65], v[166:169], v[74:77]
	v_mfma_f32_16x16x32_bf16 v[46:49], v[54:57], v[180:183], v[46:49]
	v_mfma_f32_16x16x32_bf16 v[42:45], v[62:65], v[180:183], v[42:45]
	v_mfma_f32_16x16x32_bf16 v[30:33], v[54:57], v[188:191], v[30:33]
	v_mfma_f32_16x16x32_bf16 v[26:29], v[62:65], v[188:191], v[26:29]
	v_mfma_f32_16x16x32_bf16 v[14:17], v[54:57], v[196:199], v[14:17]
	v_mfma_f32_16x16x32_bf16 v[10:13], v[62:65], v[196:199], v[10:13]
	v_mfma_f32_16x16x32_bf16 v[38:41], v[146:149], v[170:173], v[38:41]
	v_mfma_f32_16x16x32_bf16 v[34:37], v[154:157], v[170:173], v[34:37]
	v_mfma_f32_16x16x32_bf16 v[22:25], v[146:149], v[184:187], v[22:25]
	v_mfma_f32_16x16x32_bf16 v[18:21], v[154:157], v[184:187], v[18:21]
	v_mfma_f32_16x16x32_bf16 v[6:9], v[146:149], v[192:195], v[6:9]
	v_mfma_f32_16x16x32_bf16 v[2:5], v[154:157], v[192:195], v[2:5]
	v_mfma_f32_16x16x32_bf16 v[50:53], v[146:149], v[162:165], v[70:73]
	v_mfma_f32_16x16x32_bf16 v[54:57], v[154:157], v[162:165], v[66:69]
	v_mfma_f32_16x16x32_bf16 v[38:41], v[150:153], v[180:183], v[38:41]
	v_mfma_f32_16x16x32_bf16 v[34:37], v[158:161], v[180:183], v[34:37]
	v_mfma_f32_16x16x32_bf16 v[22:25], v[150:153], v[188:191], v[22:25]
	v_mfma_f32_16x16x32_bf16 v[18:21], v[158:161], v[188:191], v[18:21]
	v_mfma_f32_16x16x32_bf16 v[6:9], v[150:153], v[196:199], v[6:9]
	v_mfma_f32_16x16x32_bf16 v[2:5], v[158:161], v[196:199], v[2:5]
	v_mfma_f32_16x16x32_bf16 v[50:53], v[150:153], v[166:169], v[50:53]
	v_mfma_f32_16x16x32_bf16 v[54:57], v[158:161], v[166:169], v[54:57]
	s_setprio 0
	s_barrier
	s_add_i32 s34, 0, 0x18000
	s_add_i32 s35, 0, 0x1c000
	v_add_u32_e32 v70, s34, v205
	v_add_u32_e32 v158, s35, v205
	ds_read_b128 v[58:61], v70
	ds_read_b128 v[62:65], v70 offset:1024
	ds_read_b128 v[66:69], v70 offset:2048
	ds_read_b128 v[70:73], v70 offset:3072
	ds_read_b128 v[146:149], v158
	ds_read_b128 v[150:153], v158 offset:1024
	ds_read_b128 v[154:157], v158 offset:2048
	ds_read_b128 v[158:161], v158 offset:3072
	s_add_u32 s46, s94, 0x80000
	s_addc_u32 s47, s95, 0
	s_mov_b32 m0, s69
	v_lshl_add_u64 v[212:213], s[46:47], 0, v[0:1]
	ds_read_b128 v[162:165], v207 offset:32768
	ds_read_b128 v[166:169], v207 offset:33792
	ds_read_b128 v[170:173], v207 offset:34816
	ds_read_b128 v[180:183], v207 offset:35840
	ds_read_b128 v[184:187], v207 offset:36864
	ds_read_b128 v[188:191], v207 offset:37888
	ds_read_b128 v[192:195], v207 offset:38912
	ds_read_b128 v[196:199], v207 offset:39936
	global_load_lds_dwordx4 v[212:213], off
	s_mov_b32 m0, s72
	v_lshl_add_u64 v[212:213], s[46:47], 0, v[174:175]
	global_load_lds_dwordx4 v[212:213], off
	s_setprio 1
	s_waitcnt vmcnt(8) lgkmcnt(0)
	s_barrier
	v_mfma_f32_16x16x32_bf16 v[142:145], v[58:61], v[162:165], v[142:145]
	v_mfma_f32_16x16x32_bf16 v[138:141], v[66:69], v[162:165], v[138:141]
	v_mfma_f32_16x16x32_bf16 v[126:129], v[58:61], v[170:173], v[126:129]
	v_mfma_f32_16x16x32_bf16 v[122:125], v[66:69], v[170:173], v[122:125]
	v_mfma_f32_16x16x32_bf16 v[110:113], v[58:61], v[184:187], v[110:113]
	v_mfma_f32_16x16x32_bf16 v[106:109], v[66:69], v[184:187], v[106:109]
	v_mfma_f32_16x16x32_bf16 v[94:97], v[58:61], v[192:195], v[94:97]
	v_mfma_f32_16x16x32_bf16 v[90:93], v[66:69], v[192:195], v[90:93]
	v_mfma_f32_16x16x32_bf16 v[142:145], v[62:65], v[166:169], v[142:145]
	v_mfma_f32_16x16x32_bf16 v[138:141], v[70:73], v[166:169], v[138:141]
	v_mfma_f32_16x16x32_bf16 v[126:129], v[62:65], v[180:183], v[126:129]
	v_mfma_f32_16x16x32_bf16 v[122:125], v[70:73], v[180:183], v[122:125]
	v_mfma_f32_16x16x32_bf16 v[110:113], v[62:65], v[188:191], v[110:113]
	v_mfma_f32_16x16x32_bf16 v[106:109], v[70:73], v[188:191], v[106:109]
	v_mfma_f32_16x16x32_bf16 v[94:97], v[62:65], v[196:199], v[94:97]
	v_mfma_f32_16x16x32_bf16 v[90:93], v[70:73], v[196:199], v[90:93]
	v_mfma_f32_16x16x32_bf16 v[134:137], v[146:149], v[162:165], v[134:137]
	v_mfma_f32_16x16x32_bf16 v[130:133], v[154:157], v[162:165], v[130:133]
	v_mfma_f32_16x16x32_bf16 v[118:121], v[146:149], v[170:173], v[118:121]
	v_mfma_f32_16x16x32_bf16 v[114:117], v[154:157], v[170:173], v[114:117]
	v_mfma_f32_16x16x32_bf16 v[102:105], v[146:149], v[184:187], v[102:105]
	v_mfma_f32_16x16x32_bf16 v[98:101], v[154:157], v[184:187], v[98:101]
	v_mfma_f32_16x16x32_bf16 v[86:89], v[146:149], v[192:195], v[86:89]
	v_mfma_f32_16x16x32_bf16 v[82:85], v[154:157], v[192:195], v[82:85]
	v_mfma_f32_16x16x32_bf16 v[134:137], v[150:153], v[166:169], v[134:137]
	v_mfma_f32_16x16x32_bf16 v[130:133], v[158:161], v[166:169], v[130:133]
	v_mfma_f32_16x16x32_bf16 v[118:121], v[150:153], v[180:183], v[118:121]
	v_mfma_f32_16x16x32_bf16 v[114:117], v[158:161], v[180:183], v[114:117]
	v_mfma_f32_16x16x32_bf16 v[102:105], v[150:153], v[188:191], v[102:105]
	v_mfma_f32_16x16x32_bf16 v[98:101], v[158:161], v[188:191], v[98:101]
	v_mfma_f32_16x16x32_bf16 v[86:89], v[150:153], v[196:199], v[86:89]
	v_mfma_f32_16x16x32_bf16 v[82:85], v[158:161], v[196:199], v[82:85]
	s_setprio 0
	s_barrier
; #define PG8_STAGE(bufoff, gbase, voff) do { _Pragma("unroll") for (int _i = 0; _i < 2; ++_i) \
;         __builtin_amdgcn_global_load_lds((const unsigned*)((const char*)(gbase) + (voff)[_i]), (LAS unsigned*)(lds + (bufoff) + ldsw + _i * 8192), 16, 0, 0); } while (0)
; #define PG8_LDA(dst, b, h) do { _Pragma("unroll") for (int m = 0; m < 4; ++m) _Pragma("unroll") for (int k = 0; k < 2; ++k) dst[m][k] = *(const LAS bf16x8*)(lds + PG8_SA(b, h) + aoff + m * 2048 + k * 1024); } while (0)
; #define PG8_MMA(ai, bj, At, Bt) do { __builtin_amdgcn_s_setprio(1); _Pragma("unroll") for (int m = 0; m < 4; ++m) _Pragma("unroll") for (int n = 0; n < 2; ++n) _Pragma("unroll") for (int k = 0; k < 2; ++k) \
;         acc[ai][bj][m][n] = __builtin_amdgcn_mfma_f32_16x16x32_bf16(Bt[n][k], At[m][k], acc[ai][bj][m][n], 0, 0, 0); __builtin_amdgcn_s_setprio(0); } while (0)
; #define PG8_WAIT_V(n) asm volatile("s_waitcnt vmcnt(" #n ")" ::: "memory")
; #define PG8_WAIT_L(n) asm volatile("s_waitcnt lgkmcnt(" #n ")" ::: "memory")
; #define PG8_BAR __builtin_amdgcn_s_barrier()
; #define PG8_SCHED __builtin_amdgcn_sched_barrier(0)
; template <class Epi, int AMODE>
; __device__ __forceinline__ void gemm_phase(LAS unsigned char* lds, const Gemm g, const StaticOrder& S, const Epi& E, int stagger_us, int tid_in) {
;     ...
;             PG8_LDA(At, 1, 1); PG8_STAGE(PG8_SB(1, 0), b3, voffB); PG8_STAGE(PG8_SB(1, 1), b3 + hstepB, voffB); PG8_STAGE(PG8_SA(1, 0), a3, voffA);
;             PG8_WAIT_V(8); PG8_WAIT_L(0); PG8_BAR; PG8_MMA(1, 0, At, B0); PG8_MMA(1, 1, At, B1); PG8_BAR; PG8_SCHED;
	s_add_i32 s34, s34, s13
	v_lshl_add_u64 v[200:201], v[200:201], 0, s[74:75]
	s_mov_b32 m0, s34
	ds_read_b128 v[162:165], v207 offset:49152
	ds_read_b128 v[166:169], v207 offset:50176
	ds_read_b128 v[170:173], v207 offset:51200
	ds_read_b128 v[180:183], v207 offset:52224
	ds_read_b128 v[184:187], v207 offset:53248
	ds_read_b128 v[188:191], v207 offset:54272
	ds_read_b128 v[192:195], v207 offset:55296
	ds_read_b128 v[196:199], v207 offset:56320
	global_load_lds_dwordx4 v[200:201], off
	s_add_i32 m0, s34, 0x2000
	s_add_u32 s6, s6, 0x80080
	v_lshl_add_u64 v[200:201], v[202:203], 0, s[74:75]
	s_addc_u32 s7, s7, 0
	s_add_i32 s34, s35, s13
	global_load_lds_dwordx4 v[200:201], off
	s_mov_b32 m0, s34
	v_lshl_add_u64 v[200:201], s[6:7], 0, v[0:1]
	global_load_lds_dwordx4 v[200:201], off
	s_add_i32 m0, s34, 0x2000
	v_lshl_add_u64 v[200:201], s[6:7], 0, v[174:175]
	global_load_lds_dwordx4 v[200:201], off
	s_mov_b32 m0, s91
	v_lshl_add_u64 v[200:201], v[208:209], 0, s[74:75]
	global_load_lds_dwordx4 v[200:201], off
	s_mov_b32 m0, s96
	v_lshl_add_u64 v[200:201], v[210:211], 0, s[74:75]
	global_load_lds_dwordx4 v[200:201], off
	s_setprio 1
	s_waitcnt vmcnt(8) lgkmcnt(0)
	s_barrier
	v_mfma_f32_16x16x32_bf16 v[78:81], v[58:61], v[162:165], v[78:81]
	v_mfma_f32_16x16x32_bf16 v[74:77], v[66:69], v[162:165], v[74:77]
	v_mfma_f32_16x16x32_bf16 v[46:49], v[58:61], v[170:173], v[46:49]
	v_mfma_f32_16x16x32_bf16 v[42:45], v[66:69], v[170:173], v[42:45]
	v_mfma_f32_16x16x32_bf16 v[30:33], v[58:61], v[184:187], v[30:33]
	v_mfma_f32_16x16x32_bf16 v[26:29], v[66:69], v[184:187], v[26:29]
	v_mfma_f32_16x16x32_bf16 v[14:17], v[58:61], v[192:195], v[14:17]
	v_mfma_f32_16x16x32_bf16 v[10:13], v[66:69], v[192:195], v[10:13]
	v_mfma_f32_16x16x32_bf16 v[78:81], v[62:65], v[166:169], v[78:81]
	v_mfma_f32_16x16x32_bf16 v[74:77], v[70:73], v[166:169], v[74:77]
	v_mfma_f32_16x16x32_bf16 v[46:49], v[62:65], v[180:183], v[46:49]
	v_mfma_f32_16x16x32_bf16 v[42:45], v[70:73], v[180:183], v[42:45]
	v_mfma_f32_16x16x32_bf16 v[30:33], v[62:65], v[188:191], v[30:33]
	v_mfma_f32_16x16x32_bf16 v[26:29], v[70:73], v[188:191], v[26:29]
	v_mfma_f32_16x16x32_bf16 v[14:17], v[62:65], v[196:199], v[14:17]
	v_mfma_f32_16x16x32_bf16 v[10:13], v[70:73], v[196:199], v[10:13]
	v_mfma_f32_16x16x32_bf16 v[50:53], v[146:149], v[162:165], v[50:53]
	v_mfma_f32_16x16x32_bf16 v[70:73], v[150:153], v[166:169], v[50:53]
	v_mfma_f32_16x16x32_bf16 v[50:53], v[154:157], v[162:165], v[54:57]
	v_mfma_f32_16x16x32_bf16 v[38:41], v[146:149], v[170:173], v[38:41]
	v_mfma_f32_16x16x32_bf16 v[34:37], v[154:157], v[170:173], v[34:37]
	v_mfma_f32_16x16x32_bf16 v[22:25], v[146:149], v[184:187], v[22:25]
	v_mfma_f32_16x16x32_bf16 v[18:21], v[154:157], v[184:187], v[18:21]
	v_mfma_f32_16x16x32_bf16 v[6:9], v[146:149], v[192:195], v[6:9]
	v_mfma_f32_16x16x32_bf16 v[2:5], v[154:157], v[192:195], v[2:5]
	v_mfma_f32_16x16x32_bf16 v[66:69], v[158:161], v[166:169], v[50:53]
	v_mfma_f32_16x16x32_bf16 v[38:41], v[150:153], v[180:183], v[38:41]
	v_mfma_f32_16x16x32_bf16 v[34:37], v[158:161], v[180:183], v[34:37]
	v_mfma_f32_16x16x32_bf16 v[22:25], v[150:153], v[188:191], v[22:25]
	v_mfma_f32_16x16x32_bf16 v[18:21], v[158:161], v[188:191], v[18:21]
	v_mfma_f32_16x16x32_bf16 v[6:9], v[150:153], v[196:199], v[6:9]
	v_mfma_f32_16x16x32_bf16 v[2:5], v[158:161], v[196:199], v[2:5]
	s_setprio 0
	s_barrier
	s_add_i32 s31, s31, 2
	s_add_u32 s29, s29, 0x100
	s_addc_u32 s30, s30, 0
	s_cmp_gt_u32 s31, 29
	s_mov_b64 s[46:47], s[4:5]
	s_cbranch_scc0 .LBB0_1199
	s_and_b64 vcc, exec, s[56:57]
	s_cbranch_vccz .LBB0_1202
	s_barrier

; #define PG8_STAGE(bufoff, gbase, voff) do { _Pragma("unroll") for (int _i = 0; _i < 2; ++_i) \
;         __builtin_amdgcn_global_load_lds((const unsigned*)((const char*)(gbase) + (voff)[_i]), (LAS unsigned*)(lds + (bufoff) + ldsw + _i * 8192), 16, 0, 0); } while (0)
; #define PG8_LDA(dst, b, h) do { _Pragma("unroll") for (int m = 0; m < 4; ++m) _Pragma("unroll") for (int k = 0; k < 2; ++k) dst[m][k] = *(const LAS bf16x8*)(lds + PG8_SA(b, h) + aoff + m * 2048 + k * 1024); } while (0)
; #define PG8_LDB(dst, b, h) do { _Pragma("unroll") for (int n = 0; n < 2; ++n) _Pragma("unroll") for (int k = 0; k < 2; ++k) dst[n][k] = *(const LAS bf16x8*)(lds + PG8_SB(b, h) + boff + n * 2048 + k * 1024); } while (0)
; #define PG8_MMA(ai, bj, At, Bt) do { __builtin_amdgcn_s_setprio(1); _Pragma("unroll") for (int m = 0; m < 4; ++m) _Pragma("unroll") for (int n = 0; n < 2; ++n) _Pragma("unroll") for (int k = 0; k < 2; ++k) \
;         acc[ai][bj][m][n] = __builtin_amdgcn_mfma_f32_16x16x32_bf16(Bt[n][k], At[m][k], acc[ai][bj][m][n], 0, 0, 0); __builtin_amdgcn_s_setprio(0); } while (0)
; #define PG8_BAR __builtin_amdgcn_s_barrier()
; template <class Epi, int AMODE>
; __device__ __forceinline__ void gemm_phase(LAS unsigned char* lds, const Gemm g, const StaticOrder& S, const Epi& E, int stagger_us, int tid_in) {
;     ...
;         const bool has_next = S.next(ui + 1, nxt);
;         const char* nA = has_next ? Abase + (size_t)nxt.pm * tstepA : cA; const char* nB = has_next ? (const char*)g.Bt + (size_t)nxt.pn * tstepB : cB;
;         for (int t = 0; t < nt; t += 2) {
;             const bool last = (t == nt - 2);
;             const char* a1 = cA + (size_t)(t + 1) * kstep;
;             const char* a2 = last ? nA : cA + (size_t)(t + 2) * kstep; const char* b2 = last ? nB : cB + (size_t)(t + 2) * kstep;
;             const char* a3 = a2 + kstep; const char* b3 = b2 + kstep;
;             PG8_LDB(B0, 0, 0); PG8_LDB(B1, 0, 1); PG8_SCHED; PG8_LDA(At, 0, 0); PG8_STAGE(PG8_SA(1, 1), a1 + hstepA, voffA);
;             PG8_WAIT_V(8); PG8_WAIT_L(0); PG8_BAR; PG8_MMA(0, 0, At, B0); PG8_MMA(0, 1, At, B1); PG8_BAR; PG8_SCHED;
;     ...
;         for (int a = 0; a < 2; ++a)
; #pragma unroll
;             for (int b = 0; b < 2; ++b)
; #pragma unroll
;                 for (int m = 0; m < 4; ++m)
; #pragma unroll
;                     for (int n = 0; n < 2; ++n) acc[a][b][m][n] = (f32x4){0.f, 0.f, 0.f, 0.f};
.LBB0_1298:
	s_ashr_i32 s47, s46, 31
	s_lshl_b64 s[6:7], s[46:47], 20
	s_add_u32 s96, s9, s6
	s_addc_u32 s97, s72, s7
	s_and_b64 s[6:7], s[42:43], exec
	s_cselect_b32 s27, s97, s5
	s_cselect_b32 s28, s96, s4
	s_add_u32 s29, s4, 0x100
	v_mov_b32_e32 v2, 0
	s_addc_u32 s30, s5, 0
	s_mov_b32 s31, -2
	s_mul_i32 s6, s26, 0xfc
	v_add_u32_e32 v222, s6, v197
	v_med3_i32 v240, v222, 0, v238
	v_add_u32_e32 v241, 0xffffe000, v240
	v_lshrrev_b32_e32 v241, 12, v241
	v_add_u32_e32 v241, 4, v241
	v_lshrrev_b32_e32 v242, 11, v240
	v_mov_b32_e32 v243, 0x2000
	v_cmp_gt_i32_e64 s[6:7], v243, v222
	s_nop 1
	v_cndmask_b32_e64 v241, v241, v242, s[6:7]
	s_lshl_b32 s6, s92, 8
	s_ashr_i32 s7, s6, 31
	v_lshl_add_u64 v[236:237], s[6:7], 2, v[184:185]
	v_mad_u64_u32 v[236:237], s[6:7], v241, s15, v[236:237]
	v_med3_i32 v224, v222, 0, v238
	v_lshlrev_b32_e32 v224, 2, v224
	global_load_dword v224, v224, s[56:57]
	v_add_u32_e32 v228, 1, v222
	v_med3_i32 v228, v228, 0, v238
	v_lshlrev_b32_e32 v228, 2, v228
	global_load_dword v228, v228, s[56:57]
	v_add_u32_e32 v231, 2, v222
	v_med3_i32 v231, v231, 0, v238
	v_lshlrev_b32_e32 v231, 2, v231
	global_load_dword v231, v231, s[56:57]
	v_add_u32_e32 v233, 3, v222
	v_med3_i32 v233, v233, 0, v238
	v_lshlrev_b32_e32 v233, 2, v233
	global_load_dword v233, v233, s[56:57]
	v_add_u32_e32 v234, 4, v222
	v_med3_i32 v234, v234, 0, v238
	v_lshlrev_b32_e32 v234, 2, v234
	global_load_dword v234, v234, s[56:57]
	v_add_u32_e32 v239, 5, v222
	v_med3_i32 v239, v239, 0, v238
	v_lshlrev_b32_e32 v239, 2, v239
	global_load_dword v239, v239, s[56:57]
	v_add_u32_e32 v252, 6, v222
	v_med3_i32 v252, v252, 0, v238
	v_lshlrev_b32_e32 v252, 2, v252
	global_load_dword v252, v252, s[56:57]
	v_add_u32_e32 v253, 7, v222
	v_med3_i32 v253, v253, 0, v238
	v_lshlrev_b32_e32 v253, 2, v253
	global_load_dword v253, v253, s[56:57]
	global_load_dwordx4 v[240:243], v[236:237], off
	global_load_dwordx4 v[244:247], v[236:237], off offset:16
	global_load_dwordx4 v[248:251], v[236:237], off offset:512
	global_load_dwordx2 v[222:223], v[236:237], off offset:528
	s_nop 0
	global_load_dwordx2 v[236:237], v[236:237], off offset:536
	v_mov_b32_e32 v3, v2
	v_mov_b32_e32 v4, v2
	v_mov_b32_e32 v5, v2
	v_mov_b32_e32 v14, v2
	v_mov_b32_e32 v15, v2
	v_mov_b32_e32 v16, v2
	v_mov_b32_e32 v17, v2
	v_mov_b32_e32 v10, v2
	v_mov_b32_e32 v11, v2
	v_mov_b32_e32 v12, v2
	v_mov_b32_e32 v13, v2
	v_mov_b32_e32 v26, v2
	v_mov_b32_e32 v27, v2
	v_mov_b32_e32 v28, v2
	v_mov_b32_e32 v29, v2
	v_mov_b32_e32 v6, v2
	v_mov_b32_e32 v7, v2
	v_mov_b32_e32 v8, v2
	v_mov_b32_e32 v9, v2
	v_mov_b32_e32 v42, v2
	v_mov_b32_e32 v43, v2
	v_mov_b32_e32 v44, v2
	v_mov_b32_e32 v45, v2
	v_mov_b32_e32 v30, v2
	v_mov_b32_e32 v31, v2
	v_mov_b32_e32 v32, v2
	v_mov_b32_e32 v33, v2
	v_mov_b32_e32 v58, v2
	v_mov_b32_e32 v59, v2
	v_mov_b32_e32 v60, v2
	v_mov_b32_e32 v61, v2
	v_mov_b32_e32 v74, v2
	v_mov_b32_e32 v75, v2
	v_mov_b32_e32 v76, v2
	v_mov_b32_e32 v77, v2
	v_mov_b32_e32 v22, v2
	v_mov_b32_e32 v23, v2
	v_mov_b32_e32 v24, v2
	v_mov_b32_e32 v25, v2
	v_mov_b32_e32 v34, v2
	v_mov_b32_e32 v35, v2
	v_mov_b32_e32 v36, v2
	v_mov_b32_e32 v37, v2
	v_mov_b32_e32 v18, v2
	v_mov_b32_e32 v19, v2
	v_mov_b32_e32 v20, v2
	v_mov_b32_e32 v21, v2
	v_mov_b32_e32 v50, v2
	v_mov_b32_e32 v51, v2
	v_mov_b32_e32 v52, v2
	v_mov_b32_e32 v53, v2
	v_mov_b32_e32 v38, v2
	v_mov_b32_e32 v39, v2
	v_mov_b32_e32 v40, v2
	v_mov_b32_e32 v41, v2
	v_mov_b32_e32 v46, v2
	v_mov_b32_e32 v47, v2
	v_mov_b32_e32 v48, v2
	v_mov_b32_e32 v49, v2
	v_mov_b32_e32 v54, v2
	v_mov_b32_e32 v55, v2
	v_mov_b32_e32 v56, v2
	v_mov_b32_e32 v57, v2
	v_mov_b32_e32 v66, v2
	v_mov_b32_e32 v67, v2
	v_mov_b32_e32 v68, v2
	v_mov_b32_e32 v69, v2
	v_mov_b32_e32 v78, v2
	v_mov_b32_e32 v79, v2
	v_mov_b32_e32 v80, v2
	v_mov_b32_e32 v81, v2
	v_mov_b32_e32 v62, v2
	v_mov_b32_e32 v63, v2
	v_mov_b32_e32 v64, v2
	v_mov_b32_e32 v65, v2
	v_mov_b32_e32 v70, v2
	v_mov_b32_e32 v71, v2
	v_mov_b32_e32 v72, v2
	v_mov_b32_e32 v73, v2
	v_mov_b32_e32 v86, v2
	v_mov_b32_e32 v87, v2
	v_mov_b32_e32 v88, v2
	v_mov_b32_e32 v89, v2
	v_mov_b32_e32 v94, v2
	v_mov_b32_e32 v95, v2
	v_mov_b32_e32 v96, v2
	v_mov_b32_e32 v97, v2
	v_mov_b32_e32 v98, v2
	v_mov_b32_e32 v99, v2
	v_mov_b32_e32 v100, v2
	v_mov_b32_e32 v101, v2
	v_mov_b32_e32 v106, v2
	v_mov_b32_e32 v107, v2
	v_mov_b32_e32 v108, v2
	v_mov_b32_e32 v109, v2
	v_mov_b32_e32 v82, v2
	v_mov_b32_e32 v83, v2
	v_mov_b32_e32 v84, v2
	v_mov_b32_e32 v85, v2
	v_mov_b32_e32 v90, v2
	v_mov_b32_e32 v91, v2
	v_mov_b32_e32 v92, v2
	v_mov_b32_e32 v93, v2
	v_mov_b32_e32 v102, v2
	v_mov_b32_e32 v103, v2
	v_mov_b32_e32 v104, v2
	v_mov_b32_e32 v105, v2
	v_mov_b32_e32 v110, v2
	v_mov_b32_e32 v111, v2
	v_mov_b32_e32 v112, v2
	v_mov_b32_e32 v113, v2
	v_mov_b32_e32 v114, v2
	v_mov_b32_e32 v115, v2
	v_mov_b32_e32 v116, v2
	v_mov_b32_e32 v117, v2
	v_mov_b32_e32 v118, v2
	v_mov_b32_e32 v119, v2
	v_mov_b32_e32 v120, v2
	v_mov_b32_e32 v121, v2
	v_mov_b32_e32 v122, v2
	v_mov_b32_e32 v123, v2
	v_mov_b32_e32 v124, v2
	v_mov_b32_e32 v125, v2
	v_mov_b32_e32 v126, v2
	v_mov_b32_e32 v127, v2
	v_mov_b32_e32 v128, v2
	v_mov_b32_e32 v129, v2
	s_add_u32 s4, s44, 0x100
	s_addc_u32 s5, s45, 0
	s_add_i32 s34, 0, 0x10000
	s_cmp_eq_u32 s31, 28
	s_cselect_b32 s43, s95, s5
	s_cselect_b32 s42, s94, s4
	s_cselect_b32 s7, s27, s30
	s_cselect_b32 s6, s28, s29
	s_add_i32 s35, 0, 0x14000
	v_add_u32_e32 v142, s34, v196
	v_add_u32_e32 v158, s35, v196
	ds_read_b128 v[130:133], v142
	ds_read_b128 v[134:137], v142 offset:1024
	ds_read_b128 v[138:141], v142 offset:2048
	ds_read_b128 v[142:145], v142 offset:3072
	ds_read_b128 v[146:149], v158
	ds_read_b128 v[150:153], v158 offset:1024
	ds_read_b128 v[154:157], v158 offset:2048
	ds_read_b128 v[158:161], v158 offset:3072
	v_lshl_add_u64 v[194:195], s[44:45], 0, v[186:187]
	s_add_i32 m0, s93, 0xc000
	ds_read_b128 v[162:165], v201
	ds_read_b128 v[166:169], v201 offset:1024
	ds_read_b128 v[170:173], v201 offset:2048
	ds_read_b128 v[174:177], v201 offset:3072
	ds_read_b128 v[190:193], v201 offset:4096
	ds_read_b128 v[202:205], v201 offset:5120
	ds_read_b128 v[206:209], v201 offset:6144
	ds_read_b128 v[210:213], v201 offset:7168
	global_load_lds_dwordx4 v[194:195], off
	s_add_i32 m0, s93, 0xe000
	v_lshl_add_u64 v[194:195], s[44:45], 0, v[188:189]
	global_load_lds_dwordx4 v[194:195], off
	s_setprio 1
	s_waitcnt lgkmcnt(0)
	s_barrier
; #define PG8_STAGE(bufoff, gbase, voff) do { _Pragma("unroll") for (int _i = 0; _i < 2; ++_i) \
;         __builtin_amdgcn_global_load_lds((const unsigned*)((const char*)(gbase) + (voff)[_i]), (LAS unsigned*)(lds + (bufoff) + ldsw + _i * 8192), 16, 0, 0); } while (0)
; #define PG8_LDA(dst, b, h) do { _Pragma("unroll") for (int m = 0; m < 4; ++m) _Pragma("unroll") for (int k = 0; k < 2; ++k) dst[m][k] = *(const LAS bf16x8*)(lds + PG8_SA(b, h) + aoff + m * 2048 + k * 1024); } while (0)
; #define PG8_MMA(ai, bj, At, Bt) do { __builtin_amdgcn_s_setprio(1); _Pragma("unroll") for (int m = 0; m < 4; ++m) _Pragma("unroll") for (int n = 0; n < 2; ++n) _Pragma("unroll") for (int k = 0; k < 2; ++k) \
;         acc[ai][bj][m][n] = __builtin_amdgcn_mfma_f32_16x16x32_bf16(Bt[n][k], At[m][k], acc[ai][bj][m][n], 0, 0, 0); __builtin_amdgcn_s_setprio(0); } while (0)
; #define PG8_WAIT_V(n) asm volatile("s_waitcnt vmcnt(" #n ")" ::: "memory")
; #define PG8_WAIT_L(n) asm volatile("s_waitcnt lgkmcnt(" #n ")" ::: "memory")
; #define PG8_BAR __builtin_amdgcn_s_barrier()
; #define PG8_SCHED __builtin_amdgcn_sched_barrier(0)
; template <class Epi, int AMODE>
; __device__ __forceinline__ void gemm_phase(LAS unsigned char* lds, const Gemm g, const StaticOrder& S, const Epi& E, int stagger_us, int tid_in) {
;     ...
;             PG8_WAIT_V(8); PG8_WAIT_L(0); PG8_BAR; PG8_MMA(0, 0, At, B0); PG8_MMA(0, 1, At, B1); PG8_BAR; PG8_SCHED;
;             PG8_LDA(At, 0, 1); PG8_STAGE(PG8_SB(0, 0), b2, voffB); PG8_STAGE(PG8_SB(0, 1), b2 + hstepB, voffB); PG8_STAGE(PG8_SA(0, 0), a2, voffA);
;             PG8_WAIT_V(8); PG8_WAIT_L(0); PG8_BAR; PG8_MMA(1, 0, At, B0); PG8_MMA(1, 1, At, B1); PG8_BAR; PG8_SCHED;
	v_mfma_f32_16x16x32_bf16 v[126:129], v[130:133], v[162:165], v[126:129]
	v_mfma_f32_16x16x32_bf16 v[122:125], v[138:141], v[162:165], v[122:125]
	v_mfma_f32_16x16x32_bf16 v[118:121], v[130:133], v[170:173], v[118:121]
	v_mfma_f32_16x16x32_bf16 v[114:117], v[138:141], v[170:173], v[114:117]
	v_mfma_f32_16x16x32_bf16 v[110:113], v[130:133], v[190:193], v[110:113]
	v_mfma_f32_16x16x32_bf16 v[102:105], v[138:141], v[190:193], v[102:105]
	v_mfma_f32_16x16x32_bf16 v[90:93], v[130:133], v[206:209], v[90:93]
	v_mfma_f32_16x16x32_bf16 v[82:85], v[138:141], v[206:209], v[82:85]
	v_mfma_f32_16x16x32_bf16 v[126:129], v[134:137], v[166:169], v[126:129]
	v_mfma_f32_16x16x32_bf16 v[122:125], v[142:145], v[166:169], v[122:125]
	v_mfma_f32_16x16x32_bf16 v[118:121], v[134:137], v[174:177], v[118:121]
	v_mfma_f32_16x16x32_bf16 v[114:117], v[142:145], v[174:177], v[114:117]
	v_mfma_f32_16x16x32_bf16 v[110:113], v[134:137], v[202:205], v[110:113]
	v_mfma_f32_16x16x32_bf16 v[102:105], v[142:145], v[202:205], v[102:105]
	v_mfma_f32_16x16x32_bf16 v[90:93], v[134:137], v[210:213], v[90:93]
	v_mfma_f32_16x16x32_bf16 v[82:85], v[142:145], v[210:213], v[82:85]
	v_mfma_f32_16x16x32_bf16 v[106:109], v[146:149], v[162:165], v[106:109]
	v_mfma_f32_16x16x32_bf16 v[98:101], v[154:157], v[162:165], v[98:101]
	v_mfma_f32_16x16x32_bf16 v[94:97], v[146:149], v[170:173], v[94:97]
	v_mfma_f32_16x16x32_bf16 v[86:89], v[154:157], v[170:173], v[86:89]
	v_mfma_f32_16x16x32_bf16 v[70:73], v[146:149], v[190:193], v[70:73]
	v_mfma_f32_16x16x32_bf16 v[62:65], v[154:157], v[190:193], v[62:65]
	v_mfma_f32_16x16x32_bf16 v[78:81], v[146:149], v[206:209], v[78:81]
	v_mfma_f32_16x16x32_bf16 v[66:69], v[154:157], v[206:209], v[66:69]
	v_mfma_f32_16x16x32_bf16 v[106:109], v[150:153], v[166:169], v[106:109]
	v_mfma_f32_16x16x32_bf16 v[98:101], v[158:161], v[166:169], v[98:101]
	v_mfma_f32_16x16x32_bf16 v[94:97], v[150:153], v[174:177], v[94:97]
	v_mfma_f32_16x16x32_bf16 v[86:89], v[158:161], v[174:177], v[86:89]
	v_mfma_f32_16x16x32_bf16 v[70:73], v[150:153], v[202:205], v[70:73]
	v_mfma_f32_16x16x32_bf16 v[62:65], v[158:161], v[202:205], v[62:65]
	v_mfma_f32_16x16x32_bf16 v[78:81], v[150:153], v[210:213], v[78:81]
	v_mfma_f32_16x16x32_bf16 v[66:69], v[158:161], v[210:213], v[66:69]
	s_setprio 0
	s_barrier
	s_add_i32 s34, s34, s91
	v_lshl_add_u64 v[194:195], s[6:7], 0, v[0:1]
	s_mov_b32 m0, s34
	ds_read_b128 v[162:165], v201 offset:16384
	ds_read_b128 v[166:169], v201 offset:17408
	ds_read_b128 v[170:173], v201 offset:18432
	ds_read_b128 v[174:177], v201 offset:19456
	ds_read_b128 v[190:193], v201 offset:20480
	ds_read_b128 v[202:205], v201 offset:21504
	ds_read_b128 v[206:209], v201 offset:22528
	ds_read_b128 v[210:213], v201 offset:23552
	global_load_lds_dwordx4 v[194:195], off
	s_add_i32 m0, s34, 0x2000
	s_add_u32 s44, s6, 0x80000
	v_lshl_add_u64 v[214:215], s[6:7], 0, v[182:183]
	s_addc_u32 s45, s7, 0
	s_add_i32 s34, s35, s91
	global_load_lds_dwordx4 v[214:215], off
	v_lshl_add_u64 v[216:217], s[44:45], 0, v[0:1]
	s_mov_b32 m0, s34
	v_lshl_add_u64 v[218:219], s[42:43], 0, v[180:181]
	global_load_lds_dwordx4 v[216:217], off
	s_add_i32 m0, s34, 0x2000
	v_lshl_add_u64 v[216:217], s[44:45], 0, v[182:183]
	global_load_lds_dwordx4 v[216:217], off
	s_mov_b32 m0, s93
	v_lshl_add_u64 v[216:217], s[42:43], 0, v[178:179]
	global_load_lds_dwordx4 v[216:217], off
	s_mov_b32 m0, s83
	s_nop 0
	global_load_lds_dwordx4 v[218:219], off
	s_setprio 1
	s_waitcnt lgkmcnt(0)
	s_barrier
	v_mfma_f32_16x16x32_bf16 v[54:57], v[130:133], v[162:165], v[54:57]
	v_mfma_f32_16x16x32_bf16 v[46:49], v[138:141], v[162:165], v[46:49]
	v_mfma_f32_16x16x32_bf16 v[38:41], v[130:133], v[170:173], v[38:41]
	v_mfma_f32_16x16x32_bf16 v[50:53], v[138:141], v[170:173], v[50:53]
	v_mfma_f32_16x16x32_bf16 v[18:21], v[130:133], v[190:193], v[18:21]
	v_mfma_f32_16x16x32_bf16 v[34:37], v[138:141], v[190:193], v[34:37]
	v_mfma_f32_16x16x32_bf16 v[22:25], v[130:133], v[206:209], v[22:25]
	v_mfma_f32_16x16x32_bf16 v[74:77], v[138:141], v[206:209], v[74:77]
	v_mfma_f32_16x16x32_bf16 v[54:57], v[134:137], v[166:169], v[54:57]
	v_mfma_f32_16x16x32_bf16 v[46:49], v[142:145], v[166:169], v[46:49]
	v_mfma_f32_16x16x32_bf16 v[38:41], v[134:137], v[174:177], v[38:41]
	v_mfma_f32_16x16x32_bf16 v[50:53], v[142:145], v[174:177], v[50:53]
	v_mfma_f32_16x16x32_bf16 v[18:21], v[134:137], v[202:205], v[18:21]
	v_mfma_f32_16x16x32_bf16 v[34:37], v[142:145], v[202:205], v[34:37]
	v_mfma_f32_16x16x32_bf16 v[22:25], v[134:137], v[210:213], v[22:25]
	v_mfma_f32_16x16x32_bf16 v[74:77], v[142:145], v[210:213], v[74:77]
	v_mfma_f32_16x16x32_bf16 v[58:61], v[146:149], v[162:165], v[58:61]
	v_mfma_f32_16x16x32_bf16 v[30:33], v[154:157], v[162:165], v[30:33]
	v_mfma_f32_16x16x32_bf16 v[42:45], v[146:149], v[170:173], v[42:45]
	v_mfma_f32_16x16x32_bf16 v[6:9], v[154:157], v[170:173], v[6:9]
	v_mfma_f32_16x16x32_bf16 v[26:29], v[146:149], v[190:193], v[26:29]
	v_mfma_f32_16x16x32_bf16 v[10:13], v[154:157], v[190:193], v[10:13]
	v_mfma_f32_16x16x32_bf16 v[14:17], v[146:149], v[206:209], v[14:17]
	v_mfma_f32_16x16x32_bf16 v[2:5], v[154:157], v[206:209], v[2:5]
	v_mfma_f32_16x16x32_bf16 v[58:61], v[150:153], v[166:169], v[58:61]
	v_mfma_f32_16x16x32_bf16 v[30:33], v[158:161], v[166:169], v[30:33]
	v_mfma_f32_16x16x32_bf16 v[42:45], v[150:153], v[174:177], v[42:45]
	v_mfma_f32_16x16x32_bf16 v[6:9], v[158:161], v[174:177], v[6:9]
	v_mfma_f32_16x16x32_bf16 v[26:29], v[150:153], v[202:205], v[26:29]
	v_mfma_f32_16x16x32_bf16 v[10:13], v[158:161], v[202:205], v[10:13]
	v_mfma_f32_16x16x32_bf16 v[14:17], v[150:153], v[210:213], v[14:17]
	v_mfma_f32_16x16x32_bf16 v[2:5], v[158:161], v[210:213], v[2:5]
	s_setprio 0
	s_barrier
; #define PG8_STAGE(bufoff, gbase, voff) do { _Pragma("unroll") for (int _i = 0; _i < 2; ++_i) \
;         __builtin_amdgcn_global_load_lds((const unsigned*)((const char*)(gbase) + (voff)[_i]), (LAS unsigned*)(lds + (bufoff) + ldsw + _i * 8192), 16, 0, 0); } while (0)
; #define PG8_LDA(dst, b, h) do { _Pragma("unroll") for (int m = 0; m < 4; ++m) _Pragma("unroll") for (int k = 0; k < 2; ++k) dst[m][k] = *(const LAS bf16x8*)(lds + PG8_SA(b, h) + aoff + m * 2048 + k * 1024); } while (0)
; #define PG8_LDB(dst, b, h) do { _Pragma("unroll") for (int n = 0; n < 2; ++n) _Pragma("unroll") for (int k = 0; k < 2; ++k) dst[n][k] = *(const LAS bf16x8*)(lds + PG8_SB(b, h) + boff + n * 2048 + k * 1024); } while (0)
; #define PG8_MMA(ai, bj, At, Bt) do { __builtin_amdgcn_s_setprio(1); _Pragma("unroll") for (int m = 0; m < 4; ++m) _Pragma("unroll") for (int n = 0; n < 2; ++n) _Pragma("unroll") for (int k = 0; k < 2; ++k) \
;         acc[ai][bj][m][n] = __builtin_amdgcn_mfma_f32_16x16x32_bf16(Bt[n][k], At[m][k], acc[ai][bj][m][n], 0, 0, 0); __builtin_amdgcn_s_setprio(0); } while (0)
; #define PG8_WAIT_V(n) asm volatile("s_waitcnt vmcnt(" #n ")" ::: "memory")
; #define PG8_WAIT_L(n) asm volatile("s_waitcnt lgkmcnt(" #n ")" ::: "memory")
; #define PG8_BAR __builtin_amdgcn_s_barrier()
; #define PG8_SCHED __builtin_amdgcn_sched_barrier(0)
; template <class Epi, int AMODE>
; __device__ __forceinline__ void gemm_phase(LAS unsigned char* lds, const Gemm g, const StaticOrder& S, const Epi& E, int stagger_us, int tid_in) {
;     ...
;             PG8_LDB(B0, 1, 0); PG8_LDB(B1, 1, 1); PG8_SCHED; PG8_LDA(At, 1, 0); PG8_STAGE(PG8_SA(0, 1), a2 + hstepA, voffA);
;             PG8_WAIT_V(8); PG8_WAIT_L(0); PG8_BAR; PG8_MMA(0, 0, At, B0); PG8_MMA(0, 1, At, B1); PG8_BAR; PG8_SCHED;
;             PG8_LDA(At, 1, 1); PG8_STAGE(PG8_SB(1, 0), b3, voffB); PG8_STAGE(PG8_SB(1, 1), b3 + hstepB, voffB); PG8_STAGE(PG8_SA(1, 0), a3, voffA);
;             PG8_WAIT_V(8); PG8_WAIT_L(0); PG8_BAR; PG8_MMA(1, 0, At, B0); PG8_MMA(1, 1, At, B1); PG8_BAR; PG8_SCHED;
	s_add_i32 s34, 0, 0x18000
	s_add_i32 s35, 0, 0x1c000
	v_add_u32_e32 v142, s34, v196
	v_add_u32_e32 v158, s35, v196
	ds_read_b128 v[130:133], v142
	ds_read_b128 v[134:137], v142 offset:1024
	ds_read_b128 v[138:141], v142 offset:2048
	ds_read_b128 v[142:145], v142 offset:3072
	ds_read_b128 v[146:149], v158
	ds_read_b128 v[150:153], v158 offset:1024
	ds_read_b128 v[154:157], v158 offset:2048
	ds_read_b128 v[158:161], v158 offset:3072
	s_add_u32 s42, s42, 0x4000
	s_addc_u32 s43, s43, 0
	s_mov_b32 m0, s79
	v_lshl_add_u64 v[220:221], s[42:43], 0, v[178:179]
	ds_read_b128 v[162:165], v201 offset:32768
	ds_read_b128 v[166:169], v201 offset:33792
	ds_read_b128 v[170:173], v201 offset:34816
	ds_read_b128 v[174:177], v201 offset:35840
	ds_read_b128 v[190:193], v201 offset:36864
	ds_read_b128 v[202:205], v201 offset:37888
	ds_read_b128 v[206:209], v201 offset:38912
	ds_read_b128 v[210:213], v201 offset:39936
	global_load_lds_dwordx4 v[220:221], off
	s_mov_b32 m0, s87
	v_lshl_add_u64 v[220:221], s[42:43], 0, v[180:181]
	global_load_lds_dwordx4 v[220:221], off
	s_setprio 1
	s_waitcnt vmcnt(8) lgkmcnt(0)
	s_barrier
	v_mfma_f32_16x16x32_bf16 v[126:129], v[130:133], v[162:165], v[126:129]
	v_mfma_f32_16x16x32_bf16 v[122:125], v[138:141], v[162:165], v[122:125]
	v_mfma_f32_16x16x32_bf16 v[118:121], v[130:133], v[170:173], v[118:121]
	v_mfma_f32_16x16x32_bf16 v[114:117], v[138:141], v[170:173], v[114:117]
	v_mfma_f32_16x16x32_bf16 v[110:113], v[130:133], v[190:193], v[110:113]
	v_mfma_f32_16x16x32_bf16 v[102:105], v[138:141], v[190:193], v[102:105]
	v_mfma_f32_16x16x32_bf16 v[90:93], v[130:133], v[206:209], v[90:93]
	v_mfma_f32_16x16x32_bf16 v[82:85], v[138:141], v[206:209], v[82:85]
	v_mfma_f32_16x16x32_bf16 v[126:129], v[134:137], v[166:169], v[126:129]
	v_mfma_f32_16x16x32_bf16 v[122:125], v[142:145], v[166:169], v[122:125]
	v_mfma_f32_16x16x32_bf16 v[118:121], v[134:137], v[174:177], v[118:121]
	v_mfma_f32_16x16x32_bf16 v[114:117], v[142:145], v[174:177], v[114:117]
	v_mfma_f32_16x16x32_bf16 v[110:113], v[134:137], v[202:205], v[110:113]
	v_mfma_f32_16x16x32_bf16 v[102:105], v[142:145], v[202:205], v[102:105]
	v_mfma_f32_16x16x32_bf16 v[90:93], v[134:137], v[210:213], v[90:93]
	v_mfma_f32_16x16x32_bf16 v[82:85], v[142:145], v[210:213], v[82:85]
	v_mfma_f32_16x16x32_bf16 v[106:109], v[146:149], v[162:165], v[106:109]
	v_mfma_f32_16x16x32_bf16 v[98:101], v[154:157], v[162:165], v[98:101]
	v_mfma_f32_16x16x32_bf16 v[94:97], v[146:149], v[170:173], v[94:97]
	v_mfma_f32_16x16x32_bf16 v[86:89], v[154:157], v[170:173], v[86:89]
	v_mfma_f32_16x16x32_bf16 v[70:73], v[146:149], v[190:193], v[70:73]
	v_mfma_f32_16x16x32_bf16 v[62:65], v[154:157], v[190:193], v[62:65]
	v_mfma_f32_16x16x32_bf16 v[78:81], v[146:149], v[206:209], v[78:81]
	v_mfma_f32_16x16x32_bf16 v[66:69], v[154:157], v[206:209], v[66:69]
	v_mfma_f32_16x16x32_bf16 v[106:109], v[150:153], v[166:169], v[106:109]
	v_mfma_f32_16x16x32_bf16 v[98:101], v[158:161], v[166:169], v[98:101]
	v_mfma_f32_16x16x32_bf16 v[94:97], v[150:153], v[174:177], v[94:97]
	v_mfma_f32_16x16x32_bf16 v[86:89], v[158:161], v[174:177], v[86:89]
	v_mfma_f32_16x16x32_bf16 v[70:73], v[150:153], v[202:205], v[70:73]
	v_mfma_f32_16x16x32_bf16 v[62:65], v[158:161], v[202:205], v[62:65]
	v_mfma_f32_16x16x32_bf16 v[78:81], v[150:153], v[210:213], v[78:81]
	v_mfma_f32_16x16x32_bf16 v[66:69], v[158:161], v[210:213], v[66:69]
	s_setprio 0
	s_barrier
	s_add_i32 s34, s34, s91
	v_lshl_add_u64 v[194:195], v[194:195], 0, s[74:75]
	s_mov_b32 m0, s34
	ds_read_b128 v[162:165], v201 offset:49152
	ds_read_b128 v[166:169], v201 offset:50176
	ds_read_b128 v[170:173], v201 offset:51200
	ds_read_b128 v[174:177], v201 offset:52224
	ds_read_b128 v[190:193], v201 offset:53248
	ds_read_b128 v[202:205], v201 offset:54272
	ds_read_b128 v[206:209], v201 offset:55296
	ds_read_b128 v[210:213], v201 offset:56320
	global_load_lds_dwordx4 v[194:195], off
	s_add_i32 m0, s34, 0x2000
	s_add_u32 s6, s6, 0x80080
	v_lshl_add_u64 v[194:195], v[214:215], 0, s[74:75]
	s_addc_u32 s7, s7, 0
	s_add_i32 s34, s35, s91
	global_load_lds_dwordx4 v[194:195], off
	s_mov_b32 m0, s34
	v_lshl_add_u64 v[194:195], s[6:7], 0, v[0:1]
	global_load_lds_dwordx4 v[194:195], off
	s_add_i32 m0, s34, 0x2000
	v_lshl_add_u64 v[194:195], s[6:7], 0, v[182:183]
	global_load_lds_dwordx4 v[194:195], off
	s_mov_b32 m0, s67
	v_lshl_add_u64 v[194:195], v[216:217], 0, s[74:75]
	global_load_lds_dwordx4 v[194:195], off
	s_mov_b32 m0, s85
	v_lshl_add_u64 v[194:195], v[218:219], 0, s[74:75]
	global_load_lds_dwordx4 v[194:195], off
	s_setprio 1
	s_waitcnt vmcnt(8) lgkmcnt(0)
	s_barrier
	v_mfma_f32_16x16x32_bf16 v[54:57], v[130:133], v[162:165], v[54:57]
	v_mfma_f32_16x16x32_bf16 v[46:49], v[138:141], v[162:165], v[46:49]
	v_mfma_f32_16x16x32_bf16 v[38:41], v[130:133], v[170:173], v[38:41]
	v_mfma_f32_16x16x32_bf16 v[50:53], v[138:141], v[170:173], v[50:53]
	v_mfma_f32_16x16x32_bf16 v[18:21], v[130:133], v[190:193], v[18:21]
	v_mfma_f32_16x16x32_bf16 v[34:37], v[138:141], v[190:193], v[34:37]
	v_mfma_f32_16x16x32_bf16 v[22:25], v[130:133], v[206:209], v[22:25]
	v_mfma_f32_16x16x32_bf16 v[74:77], v[138:141], v[206:209], v[74:77]
	v_mfma_f32_16x16x32_bf16 v[54:57], v[134:137], v[166:169], v[54:57]
	v_mfma_f32_16x16x32_bf16 v[46:49], v[142:145], v[166:169], v[46:49]
	v_mfma_f32_16x16x32_bf16 v[38:41], v[134:137], v[174:177], v[38:41]
	v_mfma_f32_16x16x32_bf16 v[50:53], v[142:145], v[174:177], v[50:53]
	v_mfma_f32_16x16x32_bf16 v[18:21], v[134:137], v[202:205], v[18:21]
	v_mfma_f32_16x16x32_bf16 v[34:37], v[142:145], v[202:205], v[34:37]
	v_mfma_f32_16x16x32_bf16 v[22:25], v[134:137], v[210:213], v[22:25]
	v_mfma_f32_16x16x32_bf16 v[74:77], v[142:145], v[210:213], v[74:77]
	v_mfma_f32_16x16x32_bf16 v[58:61], v[146:149], v[162:165], v[58:61]
	v_mfma_f32_16x16x32_bf16 v[30:33], v[154:157], v[162:165], v[30:33]
	v_mfma_f32_16x16x32_bf16 v[42:45], v[146:149], v[170:173], v[42:45]
	v_mfma_f32_16x16x32_bf16 v[6:9], v[154:157], v[170:173], v[6:9]
	v_mfma_f32_16x16x32_bf16 v[26:29], v[146:149], v[190:193], v[26:29]
	v_mfma_f32_16x16x32_bf16 v[10:13], v[154:157], v[190:193], v[10:13]
	v_mfma_f32_16x16x32_bf16 v[14:17], v[146:149], v[206:209], v[14:17]
	v_mfma_f32_16x16x32_bf16 v[2:5], v[154:157], v[206:209], v[2:5]
	v_mfma_f32_16x16x32_bf16 v[58:61], v[150:153], v[166:169], v[58:61]
	v_mfma_f32_16x16x32_bf16 v[30:33], v[158:161], v[166:169], v[30:33]
	v_mfma_f32_16x16x32_bf16 v[42:45], v[150:153], v[174:177], v[42:45]
	v_mfma_f32_16x16x32_bf16 v[6:9], v[158:161], v[174:177], v[6:9]
	v_mfma_f32_16x16x32_bf16 v[26:29], v[150:153], v[202:205], v[26:29]
	v_mfma_f32_16x16x32_bf16 v[10:13], v[158:161], v[202:205], v[10:13]
	v_mfma_f32_16x16x32_bf16 v[14:17], v[150:153], v[210:213], v[14:17]
	v_mfma_f32_16x16x32_bf16 v[2:5], v[158:161], v[210:213], v[2:5]
	s_setprio 0
	s_barrier
	s_add_i32 s31, s31, 2
	s_add_u32 s29, s29, 0x100
	s_addc_u32 s30, s30, 0
	s_cmp_gt_u32 s31, 29
	s_mov_b64 s[44:45], s[4:5]
; #define PG8_STAGE(bufoff, gbase, voff) do { _Pragma("unroll") for (int _i = 0; _i < 2; ++_i) \
;         __builtin_amdgcn_global_load_lds((const unsigned*)((const char*)(gbase) + (voff)[_i]), (LAS unsigned*)(lds + (bufoff) + ldsw + _i * 8192), 16, 0, 0); } while (0)
; #define PG8_LDA(dst, b, h) do { _Pragma("unroll") for (int m = 0; m < 4; ++m) _Pragma("unroll") for (int k = 0; k < 2; ++k) dst[m][k] = *(const LAS bf16x8*)(lds + PG8_SA(b, h) + aoff + m * 2048 + k * 1024); } while (0)
; #define PG8_LDB(dst, b, h) do { _Pragma("unroll") for (int n = 0; n < 2; ++n) _Pragma("unroll") for (int k = 0; k < 2; ++k) dst[n][k] = *(const LAS bf16x8*)(lds + PG8_SB(b, h) + boff + n * 2048 + k * 1024); } while (0)
; #define PG8_MMA(ai, bj, At, Bt) do { __builtin_amdgcn_s_setprio(1); _Pragma("unroll") for (int m = 0; m < 4; ++m) _Pragma("unroll") for (int n = 0; n < 2; ++n) _Pragma("unroll") for (int k = 0; k < 2; ++k) \
;         acc[ai][bj][m][n] = __builtin_amdgcn_mfma_f32_16x16x32_bf16(Bt[n][k], At[m][k], acc[ai][bj][m][n], 0, 0, 0); __builtin_amdgcn_s_setprio(0); } while (0)
; #define PG8_WAIT_V(n) asm volatile("s_waitcnt vmcnt(" #n ")" ::: "memory")
; #define PG8_WAIT_L(n) asm volatile("s_waitcnt lgkmcnt(" #n ")" ::: "memory")
; #define PG8_BAR __builtin_amdgcn_s_barrier()
; template <class Epi, int AMODE>
; __device__ __forceinline__ void gemm_phase(LAS unsigned char* lds, const Gemm g, const StaticOrder& S, const Epi& E, int stagger_us, int tid_in) {
;     ...
;         const char* nA = has_next ? Abase + (size_t)nxt.pm * tstepA : cA; const char* nB = has_next ? (const char*)g.Bt + (size_t)nxt.pn * tstepB : cB;
;         for (int t = 0; t < nt; t += 2) {
;             const bool last = (t == nt - 2);
;             const char* a1 = cA + (size_t)(t + 1) * kstep;
;             const char* a2 = last ? nA : cA + (size_t)(t + 2) * kstep; const char* b2 = last ? nB : cB + (size_t)(t + 2) * kstep;
;             const char* a3 = a2 + kstep; const char* b3 = b2 + kstep;
;             PG8_LDB(B0, 0, 0); PG8_LDB(B1, 0, 1); PG8_SCHED; PG8_LDA(At, 0, 0); PG8_STAGE(PG8_SA(1, 1), a1 + hstepA, voffA);
;             PG8_WAIT_V(8); PG8_WAIT_L(0); PG8_BAR; PG8_MMA(0, 0, At, B0); PG8_MMA(0, 1, At, B1); PG8_BAR; PG8_SCHED;
;             PG8_LDA(At, 0, 1); PG8_STAGE(PG8_SB(0, 0), b2, voffB); PG8_STAGE(PG8_SB(0, 1), b2 + hstepB, voffB); PG8_STAGE(PG8_SA(0, 0), a2, voffA);
.LBB0_1299:
	s_add_u32 s4, s44, 0x100
	s_addc_u32 s5, s45, 0
	s_add_i32 s34, 0, 0x10000
	s_cmp_eq_u32 s31, 28
	s_cselect_b32 s43, s95, s5
	s_cselect_b32 s42, s94, s4
	s_cselect_b32 s7, s27, s30
	s_cselect_b32 s6, s28, s29
	s_add_i32 s35, 0, 0x14000
	v_add_u32_e32 v142, s34, v196
	v_add_u32_e32 v158, s35, v196
	ds_read_b128 v[130:133], v142
	ds_read_b128 v[134:137], v142 offset:1024
	ds_read_b128 v[138:141], v142 offset:2048
	ds_read_b128 v[142:145], v142 offset:3072
	ds_read_b128 v[146:149], v158
	ds_read_b128 v[150:153], v158 offset:1024
	ds_read_b128 v[154:157], v158 offset:2048
	ds_read_b128 v[158:161], v158 offset:3072
	v_lshl_add_u64 v[194:195], s[44:45], 0, v[186:187]
	s_add_i32 m0, s93, 0xc000
	ds_read_b128 v[162:165], v201
	ds_read_b128 v[166:169], v201 offset:1024
	ds_read_b128 v[170:173], v201 offset:2048
	ds_read_b128 v[174:177], v201 offset:3072
	ds_read_b128 v[190:193], v201 offset:4096
	ds_read_b128 v[202:205], v201 offset:5120
	ds_read_b128 v[206:209], v201 offset:6144
	ds_read_b128 v[210:213], v201 offset:7168
	global_load_lds_dwordx4 v[194:195], off
	s_add_i32 m0, s93, 0xe000
	v_lshl_add_u64 v[194:195], s[44:45], 0, v[188:189]
	global_load_lds_dwordx4 v[194:195], off
	s_setprio 1
	s_waitcnt vmcnt(8) lgkmcnt(0)
	s_barrier
	v_mfma_f32_16x16x32_bf16 v[126:129], v[130:133], v[162:165], v[126:129]
	v_mfma_f32_16x16x32_bf16 v[122:125], v[138:141], v[162:165], v[122:125]
	v_mfma_f32_16x16x32_bf16 v[118:121], v[130:133], v[170:173], v[118:121]
	v_mfma_f32_16x16x32_bf16 v[114:117], v[138:141], v[170:173], v[114:117]
	v_mfma_f32_16x16x32_bf16 v[110:113], v[130:133], v[190:193], v[110:113]
	v_mfma_f32_16x16x32_bf16 v[102:105], v[138:141], v[190:193], v[102:105]
	v_mfma_f32_16x16x32_bf16 v[90:93], v[130:133], v[206:209], v[90:93]
	v_mfma_f32_16x16x32_bf16 v[82:85], v[138:141], v[206:209], v[82:85]
	v_mfma_f32_16x16x32_bf16 v[126:129], v[134:137], v[166:169], v[126:129]
	v_mfma_f32_16x16x32_bf16 v[122:125], v[142:145], v[166:169], v[122:125]
	v_mfma_f32_16x16x32_bf16 v[118:121], v[134:137], v[174:177], v[118:121]
	v_mfma_f32_16x16x32_bf16 v[114:117], v[142:145], v[174:177], v[114:117]
	v_mfma_f32_16x16x32_bf16 v[110:113], v[134:137], v[202:205], v[110:113]
	v_mfma_f32_16x16x32_bf16 v[102:105], v[142:145], v[202:205], v[102:105]
	v_mfma_f32_16x16x32_bf16 v[90:93], v[134:137], v[210:213], v[90:93]
	v_mfma_f32_16x16x32_bf16 v[82:85], v[142:145], v[210:213], v[82:85]
	v_mfma_f32_16x16x32_bf16 v[106:109], v[146:149], v[162:165], v[106:109]
	v_mfma_f32_16x16x32_bf16 v[98:101], v[154:157], v[162:165], v[98:101]
	v_mfma_f32_16x16x32_bf16 v[94:97], v[146:149], v[170:173], v[94:97]
	v_mfma_f32_16x16x32_bf16 v[86:89], v[154:157], v[170:173], v[86:89]
	v_mfma_f32_16x16x32_bf16 v[70:73], v[146:149], v[190:193], v[70:73]
	v_mfma_f32_16x16x32_bf16 v[62:65], v[154:157], v[190:193], v[62:65]
	v_mfma_f32_16x16x32_bf16 v[78:81], v[146:149], v[206:209], v[78:81]
	v_mfma_f32_16x16x32_bf16 v[66:69], v[154:157], v[206:209], v[66:69]
	v_mfma_f32_16x16x32_bf16 v[106:109], v[150:153], v[166:169], v[106:109]
	v_mfma_f32_16x16x32_bf16 v[98:101], v[158:161], v[166:169], v[98:101]
	v_mfma_f32_16x16x32_bf16 v[94:97], v[150:153], v[174:177], v[94:97]
	v_mfma_f32_16x16x32_bf16 v[86:89], v[158:161], v[174:177], v[86:89]
	v_mfma_f32_16x16x32_bf16 v[70:73], v[150:153], v[202:205], v[70:73]
	v_mfma_f32_16x16x32_bf16 v[62:65], v[158:161], v[202:205], v[62:65]
	v_mfma_f32_16x16x32_bf16 v[78:81], v[150:153], v[210:213], v[78:81]
	v_mfma_f32_16x16x32_bf16 v[66:69], v[158:161], v[210:213], v[66:69]
	s_setprio 0
	s_barrier
	s_add_i32 s34, s34, s91
	v_lshl_add_u64 v[194:195], s[6:7], 0, v[0:1]
	s_mov_b32 m0, s34
	ds_read_b128 v[162:165], v201 offset:16384
	ds_read_b128 v[166:169], v201 offset:17408
	ds_read_b128 v[170:173], v201 offset:18432
	ds_read_b128 v[174:177], v201 offset:19456
	ds_read_b128 v[190:193], v201 offset:20480
	ds_read_b128 v[202:205], v201 offset:21504
	ds_read_b128 v[206:209], v201 offset:22528
	ds_read_b128 v[210:213], v201 offset:23552
	global_load_lds_dwordx4 v[194:195], off
	s_add_i32 m0, s34, 0x2000
	s_add_u32 s44, s6, 0x80000
	v_lshl_add_u64 v[214:215], s[6:7], 0, v[182:183]
	s_addc_u32 s45, s7, 0
	s_add_i32 s34, s35, s91
	global_load_lds_dwordx4 v[214:215], off
	v_lshl_add_u64 v[216:217], s[44:45], 0, v[0:1]
	s_mov_b32 m0, s34
	v_lshl_add_u64 v[218:219], s[42:43], 0, v[180:181]
	global_load_lds_dwordx4 v[216:217], off
	s_add_i32 m0, s34, 0x2000
	v_lshl_add_u64 v[216:217], s[44:45], 0, v[182:183]
	global_load_lds_dwordx4 v[216:217], off
	s_mov_b32 m0, s93
	v_lshl_add_u64 v[216:217], s[42:43], 0, v[178:179]
	global_load_lds_dwordx4 v[216:217], off
	s_mov_b32 m0, s83
	s_nop 0
	global_load_lds_dwordx4 v[218:219], off
	s_setprio 1
	s_waitcnt vmcnt(8) lgkmcnt(0)
	s_barrier
; #define PG8_STAGE(bufoff, gbase, voff) do { _Pragma("unroll") for (int _i = 0; _i < 2; ++_i) \
;         __builtin_amdgcn_global_load_lds((const unsigned*)((const char*)(gbase) + (voff)[_i]), (LAS unsigned*)(lds + (bufoff) + ldsw + _i * 8192), 16, 0, 0); } while (0)
; #define PG8_LDA(dst, b, h) do { _Pragma("unroll") for (int m = 0; m < 4; ++m) _Pragma("unroll") for (int k = 0; k < 2; ++k) dst[m][k] = *(const LAS bf16x8*)(lds + PG8_SA(b, h) + aoff + m * 2048 + k * 1024); } while (0)
; #define PG8_LDB(dst, b, h) do { _Pragma("unroll") for (int n = 0; n < 2; ++n) _Pragma("unroll") for (int k = 0; k < 2; ++k) dst[n][k] = *(const LAS bf16x8*)(lds + PG8_SB(b, h) + boff + n * 2048 + k * 1024); } while (0)
; #define PG8_MMA(ai, bj, At, Bt) do { __builtin_amdgcn_s_setprio(1); _Pragma("unroll") for (int m = 0; m < 4; ++m) _Pragma("unroll") for (int n = 0; n < 2; ++n) _Pragma("unroll") for (int k = 0; k < 2; ++k) \
;         acc[ai][bj][m][n] = __builtin_amdgcn_mfma_f32_16x16x32_bf16(Bt[n][k], At[m][k], acc[ai][bj][m][n], 0, 0, 0); __builtin_amdgcn_s_setprio(0); } while (0)
; #define PG8_WAIT_V(n) asm volatile("s_waitcnt vmcnt(" #n ")" ::: "memory")
; #define PG8_WAIT_L(n) asm volatile("s_waitcnt lgkmcnt(" #n ")" ::: "memory")
; #define PG8_BAR __builtin_amdgcn_s_barrier()
; #define PG8_SCHED __builtin_amdgcn_sched_barrier(0)
; template <class Epi, int AMODE>
; __device__ __forceinline__ void gemm_phase(LAS unsigned char* lds, const Gemm g, const StaticOrder& S, const Epi& E, int stagger_us, int tid_in) {
;     ...
;             PG8_WAIT_V(8); PG8_WAIT_L(0); PG8_BAR; PG8_MMA(1, 0, At, B0); PG8_MMA(1, 1, At, B1); PG8_BAR; PG8_SCHED;
;             PG8_LDB(B0, 1, 0); PG8_LDB(B1, 1, 1); PG8_SCHED; PG8_LDA(At, 1, 0); PG8_STAGE(PG8_SA(0, 1), a2 + hstepA, voffA);
;             PG8_WAIT_V(8); PG8_WAIT_L(0); PG8_BAR; PG8_MMA(0, 0, At, B0); PG8_MMA(0, 1, At, B1); PG8_BAR; PG8_SCHED;
	v_mfma_f32_16x16x32_bf16 v[54:57], v[130:133], v[162:165], v[54:57]
	v_mfma_f32_16x16x32_bf16 v[46:49], v[138:141], v[162:165], v[46:49]
	v_mfma_f32_16x16x32_bf16 v[38:41], v[130:133], v[170:173], v[38:41]
	v_mfma_f32_16x16x32_bf16 v[50:53], v[138:141], v[170:173], v[50:53]
	v_mfma_f32_16x16x32_bf16 v[18:21], v[130:133], v[190:193], v[18:21]
	v_mfma_f32_16x16x32_bf16 v[34:37], v[138:141], v[190:193], v[34:37]
	v_mfma_f32_16x16x32_bf16 v[22:25], v[130:133], v[206:209], v[22:25]
	v_mfma_f32_16x16x32_bf16 v[74:77], v[138:141], v[206:209], v[74:77]
	v_mfma_f32_16x16x32_bf16 v[54:57], v[134:137], v[166:169], v[54:57]
	v_mfma_f32_16x16x32_bf16 v[46:49], v[142:145], v[166:169], v[46:49]
	v_mfma_f32_16x16x32_bf16 v[38:41], v[134:137], v[174:177], v[38:41]
	v_mfma_f32_16x16x32_bf16 v[50:53], v[142:145], v[174:177], v[50:53]
	v_mfma_f32_16x16x32_bf16 v[18:21], v[134:137], v[202:205], v[18:21]
	v_mfma_f32_16x16x32_bf16 v[34:37], v[142:145], v[202:205], v[34:37]
	v_mfma_f32_16x16x32_bf16 v[22:25], v[134:137], v[210:213], v[22:25]
	v_mfma_f32_16x16x32_bf16 v[74:77], v[142:145], v[210:213], v[74:77]
	v_mfma_f32_16x16x32_bf16 v[58:61], v[146:149], v[162:165], v[58:61]
	v_mfma_f32_16x16x32_bf16 v[30:33], v[154:157], v[162:165], v[30:33]
	v_mfma_f32_16x16x32_bf16 v[42:45], v[146:149], v[170:173], v[42:45]
	v_mfma_f32_16x16x32_bf16 v[6:9], v[154:157], v[170:173], v[6:9]
	v_mfma_f32_16x16x32_bf16 v[26:29], v[146:149], v[190:193], v[26:29]
	v_mfma_f32_16x16x32_bf16 v[10:13], v[154:157], v[190:193], v[10:13]
	v_mfma_f32_16x16x32_bf16 v[14:17], v[146:149], v[206:209], v[14:17]
	v_mfma_f32_16x16x32_bf16 v[2:5], v[154:157], v[206:209], v[2:5]
	v_mfma_f32_16x16x32_bf16 v[58:61], v[150:153], v[166:169], v[58:61]
	v_mfma_f32_16x16x32_bf16 v[30:33], v[158:161], v[166:169], v[30:33]
	v_mfma_f32_16x16x32_bf16 v[42:45], v[150:153], v[174:177], v[42:45]
	v_mfma_f32_16x16x32_bf16 v[6:9], v[158:161], v[174:177], v[6:9]
	v_mfma_f32_16x16x32_bf16 v[26:29], v[150:153], v[202:205], v[26:29]
	v_mfma_f32_16x16x32_bf16 v[10:13], v[158:161], v[202:205], v[10:13]
	v_mfma_f32_16x16x32_bf16 v[14:17], v[150:153], v[210:213], v[14:17]
	v_mfma_f32_16x16x32_bf16 v[2:5], v[158:161], v[210:213], v[2:5]
	s_setprio 0
	s_barrier
	s_add_i32 s34, 0, 0x18000
	s_add_i32 s35, 0, 0x1c000
	v_add_u32_e32 v142, s34, v196
	v_add_u32_e32 v158, s35, v196
	ds_read_b128 v[130:133], v142
	ds_read_b128 v[134:137], v142 offset:1024
	ds_read_b128 v[138:141], v142 offset:2048
	ds_read_b128 v[142:145], v142 offset:3072
	ds_read_b128 v[146:149], v158
	ds_read_b128 v[150:153], v158 offset:1024
	ds_read_b128 v[154:157], v158 offset:2048
	ds_read_b128 v[158:161], v158 offset:3072
	s_add_u32 s42, s42, 0x4000
	s_addc_u32 s43, s43, 0
	s_mov_b32 m0, s79
	v_lshl_add_u64 v[220:221], s[42:43], 0, v[178:179]
	ds_read_b128 v[162:165], v201 offset:32768
	ds_read_b128 v[166:169], v201 offset:33792
	ds_read_b128 v[170:173], v201 offset:34816
	ds_read_b128 v[174:177], v201 offset:35840
	ds_read_b128 v[190:193], v201 offset:36864
	ds_read_b128 v[202:205], v201 offset:37888
	ds_read_b128 v[206:209], v201 offset:38912
	ds_read_b128 v[210:213], v201 offset:39936
	global_load_lds_dwordx4 v[220:221], off
	s_mov_b32 m0, s87
	v_lshl_add_u64 v[220:221], s[42:43], 0, v[180:181]
	global_load_lds_dwordx4 v[220:221], off
	s_setprio 1
	s_waitcnt vmcnt(8) lgkmcnt(0)
	s_barrier
	v_mfma_f32_16x16x32_bf16 v[126:129], v[130:133], v[162:165], v[126:129]
	v_mfma_f32_16x16x32_bf16 v[122:125], v[138:141], v[162:165], v[122:125]
	v_mfma_f32_16x16x32_bf16 v[118:121], v[130:133], v[170:173], v[118:121]
	v_mfma_f32_16x16x32_bf16 v[114:117], v[138:141], v[170:173], v[114:117]
	v_mfma_f32_16x16x32_bf16 v[110:113], v[130:133], v[190:193], v[110:113]
	v_mfma_f32_16x16x32_bf16 v[102:105], v[138:141], v[190:193], v[102:105]
	v_mfma_f32_16x16x32_bf16 v[90:93], v[130:133], v[206:209], v[90:93]
	v_mfma_f32_16x16x32_bf16 v[82:85], v[138:141], v[206:209], v[82:85]
	v_mfma_f32_16x16x32_bf16 v[126:129], v[134:137], v[166:169], v[126:129]
	v_mfma_f32_16x16x32_bf16 v[122:125], v[142:145], v[166:169], v[122:125]
	v_mfma_f32_16x16x32_bf16 v[118:121], v[134:137], v[174:177], v[118:121]
	v_mfma_f32_16x16x32_bf16 v[114:117], v[142:145], v[174:177], v[114:117]
	v_mfma_f32_16x16x32_bf16 v[110:113], v[134:137], v[202:205], v[110:113]
	v_mfma_f32_16x16x32_bf16 v[102:105], v[142:145], v[202:205], v[102:105]
	v_mfma_f32_16x16x32_bf16 v[90:93], v[134:137], v[210:213], v[90:93]
	v_mfma_f32_16x16x32_bf16 v[82:85], v[142:145], v[210:213], v[82:85]
	v_mfma_f32_16x16x32_bf16 v[106:109], v[146:149], v[162:165], v[106:109]
	v_mfma_f32_16x16x32_bf16 v[98:101], v[154:157], v[162:165], v[98:101]
	v_mfma_f32_16x16x32_bf16 v[94:97], v[146:149], v[170:173], v[94:97]
	v_mfma_f32_16x16x32_bf16 v[86:89], v[154:157], v[170:173], v[86:89]
	v_mfma_f32_16x16x32_bf16 v[70:73], v[146:149], v[190:193], v[70:73]
	v_mfma_f32_16x16x32_bf16 v[62:65], v[154:157], v[190:193], v[62:65]
	v_mfma_f32_16x16x32_bf16 v[78:81], v[146:149], v[206:209], v[78:81]
	v_mfma_f32_16x16x32_bf16 v[66:69], v[154:157], v[206:209], v[66:69]
	v_mfma_f32_16x16x32_bf16 v[106:109], v[150:153], v[166:169], v[106:109]
	v_mfma_f32_16x16x32_bf16 v[98:101], v[158:161], v[166:169], v[98:101]
	v_mfma_f32_16x16x32_bf16 v[94:97], v[150:153], v[174:177], v[94:97]
	v_mfma_f32_16x16x32_bf16 v[86:89], v[158:161], v[174:177], v[86:89]
	v_mfma_f32_16x16x32_bf16 v[70:73], v[150:153], v[202:205], v[70:73]
	v_mfma_f32_16x16x32_bf16 v[62:65], v[158:161], v[202:205], v[62:65]
	v_mfma_f32_16x16x32_bf16 v[78:81], v[150:153], v[210:213], v[78:81]
	v_mfma_f32_16x16x32_bf16 v[66:69], v[158:161], v[210:213], v[66:69]
	s_setprio 0
	s_barrier
; #define PG8_STAGE(bufoff, gbase, voff) do { _Pragma("unroll") for (int _i = 0; _i < 2; ++_i) \
;         __builtin_amdgcn_global_load_lds((const unsigned*)((const char*)(gbase) + (voff)[_i]), (LAS unsigned*)(lds + (bufoff) + ldsw + _i * 8192), 16, 0, 0); } while (0)
; #define PG8_LDA(dst, b, h) do { _Pragma("unroll") for (int m = 0; m < 4; ++m) _Pragma("unroll") for (int k = 0; k < 2; ++k) dst[m][k] = *(const LAS bf16x8*)(lds + PG8_SA(b, h) + aoff + m * 2048 + k * 1024); } while (0)
; #define PG8_MMA(ai, bj, At, Bt) do { __builtin_amdgcn_s_setprio(1); _Pragma("unroll") for (int m = 0; m < 4; ++m) _Pragma("unroll") for (int n = 0; n < 2; ++n) _Pragma("unroll") for (int k = 0; k < 2; ++k) \
;         acc[ai][bj][m][n] = __builtin_amdgcn_mfma_f32_16x16x32_bf16(Bt[n][k], At[m][k], acc[ai][bj][m][n], 0, 0, 0); __builtin_amdgcn_s_setprio(0); } while (0)
; #define PG8_WAIT_V(n) asm volatile("s_waitcnt vmcnt(" #n ")" ::: "memory")
; #define PG8_WAIT_L(n) asm volatile("s_waitcnt lgkmcnt(" #n ")" ::: "memory")
; #define PG8_BAR __builtin_amdgcn_s_barrier()
; #define PG8_SCHED __builtin_amdgcn_sched_barrier(0)
; template <class Epi, int AMODE>
; __device__ __forceinline__ void gemm_phase(LAS unsigned char* lds, const Gemm g, const StaticOrder& S, const Epi& E, int stagger_us, int tid_in) {
;     ...
;             PG8_LDA(At, 1, 1); PG8_STAGE(PG8_SB(1, 0), b3, voffB); PG8_STAGE(PG8_SB(1, 1), b3 + hstepB, voffB); PG8_STAGE(PG8_SA(1, 0), a3, voffA);
;             PG8_WAIT_V(8); PG8_WAIT_L(0); PG8_BAR; PG8_MMA(1, 0, At, B0); PG8_MMA(1, 1, At, B1); PG8_BAR; PG8_SCHED;
	s_add_i32 s34, s34, s91
	v_lshl_add_u64 v[194:195], v[194:195], 0, s[74:75]
	s_mov_b32 m0, s34
	ds_read_b128 v[162:165], v201 offset:49152
	ds_read_b128 v[166:169], v201 offset:50176
	ds_read_b128 v[170:173], v201 offset:51200
	ds_read_b128 v[174:177], v201 offset:52224
	ds_read_b128 v[190:193], v201 offset:53248
	ds_read_b128 v[202:205], v201 offset:54272
	ds_read_b128 v[206:209], v201 offset:55296
	ds_read_b128 v[210:213], v201 offset:56320
	global_load_lds_dwordx4 v[194:195], off
	s_add_i32 m0, s34, 0x2000
	s_add_u32 s6, s6, 0x80080
	v_lshl_add_u64 v[194:195], v[214:215], 0, s[74:75]
	s_addc_u32 s7, s7, 0
	s_add_i32 s34, s35, s91
	global_load_lds_dwordx4 v[194:195], off
	s_mov_b32 m0, s34
	v_lshl_add_u64 v[194:195], s[6:7], 0, v[0:1]
	global_load_lds_dwordx4 v[194:195], off
	s_add_i32 m0, s34, 0x2000
	v_lshl_add_u64 v[194:195], s[6:7], 0, v[182:183]
	global_load_lds_dwordx4 v[194:195], off
	s_mov_b32 m0, s67
	v_lshl_add_u64 v[194:195], v[216:217], 0, s[74:75]
	global_load_lds_dwordx4 v[194:195], off
	s_mov_b32 m0, s85
	v_lshl_add_u64 v[194:195], v[218:219], 0, s[74:75]
	global_load_lds_dwordx4 v[194:195], off
	s_setprio 1
	s_waitcnt vmcnt(8) lgkmcnt(0)
	s_barrier
	v_mfma_f32_16x16x32_bf16 v[54:57], v[130:133], v[162:165], v[54:57]
	v_mfma_f32_16x16x32_bf16 v[46:49], v[138:141], v[162:165], v[46:49]
	v_mfma_f32_16x16x32_bf16 v[38:41], v[130:133], v[170:173], v[38:41]
	v_mfma_f32_16x16x32_bf16 v[50:53], v[138:141], v[170:173], v[50:53]
	v_mfma_f32_16x16x32_bf16 v[18:21], v[130:133], v[190:193], v[18:21]
	v_mfma_f32_16x16x32_bf16 v[34:37], v[138:141], v[190:193], v[34:37]
	v_mfma_f32_16x16x32_bf16 v[22:25], v[130:133], v[206:209], v[22:25]
	v_mfma_f32_16x16x32_bf16 v[74:77], v[138:141], v[206:209], v[74:77]
	v_mfma_f32_16x16x32_bf16 v[54:57], v[134:137], v[166:169], v[54:57]
	v_mfma_f32_16x16x32_bf16 v[46:49], v[142:145], v[166:169], v[46:49]
	v_mfma_f32_16x16x32_bf16 v[38:41], v[134:137], v[174:177], v[38:41]
	v_mfma_f32_16x16x32_bf16 v[50:53], v[142:145], v[174:177], v[50:53]
	v_mfma_f32_16x16x32_bf16 v[18:21], v[134:137], v[202:205], v[18:21]
	v_mfma_f32_16x16x32_bf16 v[34:37], v[142:145], v[202:205], v[34:37]
	v_mfma_f32_16x16x32_bf16 v[22:25], v[134:137], v[210:213], v[22:25]
	v_mfma_f32_16x16x32_bf16 v[74:77], v[142:145], v[210:213], v[74:77]
	v_mfma_f32_16x16x32_bf16 v[58:61], v[146:149], v[162:165], v[58:61]
	v_mfma_f32_16x16x32_bf16 v[30:33], v[154:157], v[162:165], v[30:33]
	v_mfma_f32_16x16x32_bf16 v[42:45], v[146:149], v[170:173], v[42:45]
	v_mfma_f32_16x16x32_bf16 v[6:9], v[154:157], v[170:173], v[6:9]
	v_mfma_f32_16x16x32_bf16 v[26:29], v[146:149], v[190:193], v[26:29]
	v_mfma_f32_16x16x32_bf16 v[10:13], v[154:157], v[190:193], v[10:13]
	v_mfma_f32_16x16x32_bf16 v[14:17], v[146:149], v[206:209], v[14:17]
	v_mfma_f32_16x16x32_bf16 v[2:5], v[154:157], v[206:209], v[2:5]
	v_mfma_f32_16x16x32_bf16 v[58:61], v[150:153], v[166:169], v[58:61]
	v_mfma_f32_16x16x32_bf16 v[30:33], v[158:161], v[166:169], v[30:33]
	v_mfma_f32_16x16x32_bf16 v[42:45], v[150:153], v[174:177], v[42:45]
	v_mfma_f32_16x16x32_bf16 v[6:9], v[158:161], v[174:177], v[6:9]
	v_mfma_f32_16x16x32_bf16 v[26:29], v[150:153], v[202:205], v[26:29]
	v_mfma_f32_16x16x32_bf16 v[10:13], v[158:161], v[202:205], v[10:13]
	v_mfma_f32_16x16x32_bf16 v[14:17], v[150:153], v[210:213], v[14:17]
	v_mfma_f32_16x16x32_bf16 v[2:5], v[158:161], v[210:213], v[2:5]
	s_setprio 0
	s_barrier
	s_add_i32 s31, s31, 2
	s_add_u32 s29, s29, 0x100
	s_addc_u32 s30, s30, 0
	s_cmp_gt_u32 s31, 29
	s_mov_b64 s[44:45], s[4:5]
	s_cbranch_scc0 .LBB0_1299
	s_and_b64 vcc, exec, s[48:49]
	s_cbranch_vccz .LBB0_1302
	s_barrier

; #define PG8_STAGE(bufoff, gbase, voff) do { _Pragma("unroll") for (int _i = 0; _i < 2; ++_i) \
;         __builtin_amdgcn_global_load_lds((const unsigned*)((const char*)(gbase) + (voff)[_i]), (LAS unsigned*)(lds + (bufoff) + ldsw + _i * 8192), 16, 0, 0); } while (0)
; #define PG8_LDA(dst, b, h) do { _Pragma("unroll") for (int m = 0; m < 4; ++m) _Pragma("unroll") for (int k = 0; k < 2; ++k) dst[m][k] = *(const LAS bf16x8*)(lds + PG8_SA(b, h) + aoff + m * 2048 + k * 1024); } while (0)
; #define PG8_LDB(dst, b, h) do { _Pragma("unroll") for (int n = 0; n < 2; ++n) _Pragma("unroll") for (int k = 0; k < 2; ++k) dst[n][k] = *(const LAS bf16x8*)(lds + PG8_SB(b, h) + boff + n * 2048 + k * 1024); } while (0)
; #define PG8_MMA(ai, bj, At, Bt) do { __builtin_amdgcn_s_setprio(1); _Pragma("unroll") for (int m = 0; m < 4; ++m) _Pragma("unroll") for (int n = 0; n < 2; ++n) _Pragma("unroll") for (int k = 0; k < 2; ++k) \
;         acc[ai][bj][m][n] = __builtin_amdgcn_mfma_f32_16x16x32_bf16(Bt[n][k], At[m][k], acc[ai][bj][m][n], 0, 0, 0); __builtin_amdgcn_s_setprio(0); } while (0)
; #define PG8_WAIT_V(n) asm volatile("s_waitcnt vmcnt(" #n ")" ::: "memory")
; #define PG8_WAIT_L(n) asm volatile("s_waitcnt lgkmcnt(" #n ")" ::: "memory")
; #define PG8_BAR __builtin_amdgcn_s_barrier()
; template <class Epi, int AMODE>
; __device__ __forceinline__ void gemm_phase(LAS unsigned char* lds, const Gemm g, const StaticOrder& S, const Epi& E, int stagger_us, int tid_in) {
;     ...
;         const char* nA = has_next ? Abase + (size_t)nxt.pm * tstepA : cA; const char* nB = has_next ? (const char*)g.Bt + (size_t)nxt.pn * tstepB : cB;
;         for (int t = 0; t < nt; t += 2) {
;             const bool last = (t == nt - 2);
;             const char* a1 = cA + (size_t)(t + 1) * kstep;
;             const char* a2 = last ? nA : cA + (size_t)(t + 2) * kstep; const char* b2 = last ? nB : cB + (size_t)(t + 2) * kstep;
;             const char* a3 = a2 + kstep; const char* b3 = b2 + kstep;
;             PG8_LDB(B0, 0, 0); PG8_LDB(B1, 0, 1); PG8_SCHED; PG8_LDA(At, 0, 0); PG8_STAGE(PG8_SA(1, 1), a1 + hstepA, voffA);
;             PG8_WAIT_V(8); PG8_WAIT_L(0); PG8_BAR; PG8_MMA(0, 0, At, B0); PG8_MMA(0, 1, At, B1); PG8_BAR; PG8_SCHED;
;             PG8_LDA(At, 0, 1); PG8_STAGE(PG8_SB(0, 0), b2, voffB); PG8_STAGE(PG8_SB(0, 1), b2 + hstepB, voffB); PG8_STAGE(PG8_SA(0, 0), a2, voffA);
.LBB0_1476:
	s_add_u32 s4, s54, 0x100
	s_addc_u32 s5, s55, 0
	s_add_i32 s30, 0, 0x10000
	s_cmpk_eq_i32 s29, 0x52
	s_cselect_b32 s57, s41, s5
	s_cselect_b32 s56, s40, s4
	s_cselect_b32 s7, s53, s28
	s_cselect_b32 s6, s52, s27
	s_add_i32 s34, 0, 0x14000
	v_add_u32_e32 v102, s30, v162
	v_add_u32_e32 v165, s34, v162
	ds_read_b128 v[66:69], v102
	ds_read_b128 v[70:73], v102 offset:1024
	ds_read_b128 v[74:77], v102 offset:2048
	ds_read_b128 v[102:105], v102 offset:3072
	ds_read_b128 v[152:155], v165
	ds_read_b128 v[156:159], v165 offset:1024
	ds_read_b128 v[166:169], v165 offset:2048
	ds_read_b128 v[170:173], v165 offset:3072
	v_lshl_add_u64 v[206:207], s[54:55], 0, v[148:149]
	s_add_i32 m0, s13, 0xc000
	ds_read_b128 v[174:177], v164
	ds_read_b128 v[178:181], v164 offset:1024
	ds_read_b128 v[182:185], v164 offset:2048
	ds_read_b128 v[186:189], v164 offset:3072
	ds_read_b128 v[190:193], v164 offset:4096
	ds_read_b128 v[194:197], v164 offset:5120
	ds_read_b128 v[198:201], v164 offset:6144
	ds_read_b128 v[202:205], v164 offset:7168
	global_load_lds_dwordx4 v[206:207], off
	s_add_i32 m0, s13, 0xe000
	v_lshl_add_u64 v[206:207], s[54:55], 0, v[150:151]
	global_load_lds_dwordx4 v[206:207], off
	s_setprio 1
	s_waitcnt vmcnt(8) lgkmcnt(0)
	s_barrier
	v_mfma_f32_16x16x32_bf16 v[142:145], v[66:69], v[174:177], v[142:145]
	v_mfma_f32_16x16x32_bf16 v[138:141], v[74:77], v[174:177], v[138:141]
	v_mfma_f32_16x16x32_bf16 v[134:137], v[66:69], v[182:185], v[134:137]
	v_mfma_f32_16x16x32_bf16 v[130:133], v[74:77], v[182:185], v[130:133]
	v_mfma_f32_16x16x32_bf16 v[110:113], v[66:69], v[190:193], v[110:113]
	v_mfma_f32_16x16x32_bf16 v[106:109], v[74:77], v[190:193], v[106:109]
	v_mfma_f32_16x16x32_bf16 v[98:101], v[66:69], v[198:201], v[98:101]
	v_mfma_f32_16x16x32_bf16 v[94:97], v[74:77], v[198:201], v[94:97]
	v_mfma_f32_16x16x32_bf16 v[142:145], v[70:73], v[178:181], v[142:145]
	v_mfma_f32_16x16x32_bf16 v[138:141], v[102:105], v[178:181], v[138:141]
	v_mfma_f32_16x16x32_bf16 v[134:137], v[70:73], v[186:189], v[134:137]
	v_mfma_f32_16x16x32_bf16 v[130:133], v[102:105], v[186:189], v[130:133]
	v_mfma_f32_16x16x32_bf16 v[110:113], v[70:73], v[194:197], v[110:113]
	v_mfma_f32_16x16x32_bf16 v[106:109], v[102:105], v[194:197], v[106:109]
	v_mfma_f32_16x16x32_bf16 v[98:101], v[70:73], v[202:205], v[98:101]
	v_mfma_f32_16x16x32_bf16 v[94:97], v[102:105], v[202:205], v[94:97]
	v_mfma_f32_16x16x32_bf16 v[126:129], v[152:155], v[174:177], v[126:129]
	v_mfma_f32_16x16x32_bf16 v[122:125], v[166:169], v[174:177], v[122:125]
	v_mfma_f32_16x16x32_bf16 v[118:121], v[152:155], v[182:185], v[118:121]
	v_mfma_f32_16x16x32_bf16 v[114:117], v[166:169], v[182:185], v[114:117]
	v_mfma_f32_16x16x32_bf16 v[90:93], v[152:155], v[190:193], v[90:93]
	v_mfma_f32_16x16x32_bf16 v[86:89], v[166:169], v[190:193], v[86:89]
	v_mfma_f32_16x16x32_bf16 v[82:85], v[152:155], v[198:201], v[82:85]
	v_mfma_f32_16x16x32_bf16 v[78:81], v[166:169], v[198:201], v[78:81]
	v_mfma_f32_16x16x32_bf16 v[126:129], v[156:159], v[178:181], v[126:129]
	v_mfma_f32_16x16x32_bf16 v[122:125], v[170:173], v[178:181], v[122:125]
	v_mfma_f32_16x16x32_bf16 v[118:121], v[156:159], v[186:189], v[118:121]
	v_mfma_f32_16x16x32_bf16 v[114:117], v[170:173], v[186:189], v[114:117]
	v_mfma_f32_16x16x32_bf16 v[90:93], v[156:159], v[194:197], v[90:93]
	v_mfma_f32_16x16x32_bf16 v[86:89], v[170:173], v[194:197], v[86:89]
	v_mfma_f32_16x16x32_bf16 v[82:85], v[156:159], v[202:205], v[82:85]
	v_mfma_f32_16x16x32_bf16 v[78:81], v[170:173], v[202:205], v[78:81]
	s_setprio 0
	s_barrier
	s_add_i32 s30, s30, s12
	v_lshl_add_u64 v[206:207], s[6:7], 0, v[0:1]
	s_mov_b32 m0, s30
	ds_read_b128 v[174:177], v164 offset:16384
	ds_read_b128 v[178:181], v164 offset:17408
	ds_read_b128 v[182:185], v164 offset:18432
	ds_read_b128 v[186:189], v164 offset:19456
	ds_read_b128 v[190:193], v164 offset:20480
	ds_read_b128 v[194:197], v164 offset:21504
	ds_read_b128 v[198:201], v164 offset:22528
	ds_read_b128 v[202:205], v164 offset:23552
	global_load_lds_dwordx4 v[206:207], off
	s_add_i32 m0, s30, 0x2000
	s_add_u32 s30, s6, 0x158000
	v_lshl_add_u64 v[208:209], s[6:7], 0, v[146:147]
	s_addc_u32 s31, s7, 0
	s_add_i32 s34, s34, s12
	global_load_lds_dwordx4 v[208:209], off
	v_lshl_add_u64 v[210:211], s[30:31], 0, v[0:1]
	s_mov_b32 m0, s34
	v_lshl_add_u64 v[212:213], s[56:57], 0, v[146:147]
	global_load_lds_dwordx4 v[210:211], off
	s_add_i32 m0, s34, 0x2000
	v_lshl_add_u64 v[210:211], s[30:31], 0, v[146:147]
	global_load_lds_dwordx4 v[210:211], off
	s_mov_b32 m0, s13
	v_lshl_add_u64 v[210:211], s[56:57], 0, v[0:1]
	global_load_lds_dwordx4 v[210:211], off
	s_mov_b32 m0, s24
	s_nop 0
	global_load_lds_dwordx4 v[212:213], off
	s_setprio 1
	s_waitcnt vmcnt(8) lgkmcnt(0)
	s_barrier
; #define PG8_STAGE(bufoff, gbase, voff) do { _Pragma("unroll") for (int _i = 0; _i < 2; ++_i) \
;         __builtin_amdgcn_global_load_lds((const unsigned*)((const char*)(gbase) + (voff)[_i]), (LAS unsigned*)(lds + (bufoff) + ldsw + _i * 8192), 16, 0, 0); } while (0)
; #define PG8_LDA(dst, b, h) do { _Pragma("unroll") for (int m = 0; m < 4; ++m) _Pragma("unroll") for (int k = 0; k < 2; ++k) dst[m][k] = *(const LAS bf16x8*)(lds + PG8_SA(b, h) + aoff + m * 2048 + k * 1024); } while (0)
; #define PG8_LDB(dst, b, h) do { _Pragma("unroll") for (int n = 0; n < 2; ++n) _Pragma("unroll") for (int k = 0; k < 2; ++k) dst[n][k] = *(const LAS bf16x8*)(lds + PG8_SB(b, h) + boff + n * 2048 + k * 1024); } while (0)
; #define PG8_MMA(ai, bj, At, Bt) do { __builtin_amdgcn_s_setprio(1); _Pragma("unroll") for (int m = 0; m < 4; ++m) _Pragma("unroll") for (int n = 0; n < 2; ++n) _Pragma("unroll") for (int k = 0; k < 2; ++k) \
;         acc[ai][bj][m][n] = __builtin_amdgcn_mfma_f32_16x16x32_bf16(Bt[n][k], At[m][k], acc[ai][bj][m][n], 0, 0, 0); __builtin_amdgcn_s_setprio(0); } while (0)
; #define PG8_WAIT_V(n) asm volatile("s_waitcnt vmcnt(" #n ")" ::: "memory")
; #define PG8_WAIT_L(n) asm volatile("s_waitcnt lgkmcnt(" #n ")" ::: "memory")
; #define PG8_BAR __builtin_amdgcn_s_barrier()
; #define PG8_SCHED __builtin_amdgcn_sched_barrier(0)
; template <class Epi, int AMODE>
; __device__ __forceinline__ void gemm_phase(LAS unsigned char* lds, const Gemm g, const StaticOrder& S, const Epi& E, int stagger_us, int tid_in) {
;     ...
;             PG8_WAIT_V(8); PG8_WAIT_L(0); PG8_BAR; PG8_MMA(1, 0, At, B0); PG8_MMA(1, 1, At, B1); PG8_BAR; PG8_SCHED;
;             PG8_LDB(B0, 1, 0); PG8_LDB(B1, 1, 1); PG8_SCHED; PG8_LDA(At, 1, 0); PG8_STAGE(PG8_SA(0, 1), a2 + hstepA, voffA);
;             PG8_WAIT_V(8); PG8_WAIT_L(0); PG8_BAR; PG8_MMA(0, 0, At, B0); PG8_MMA(0, 1, At, B1); PG8_BAR; PG8_SCHED;
	v_mfma_f32_16x16x32_bf16 v[62:65], v[66:69], v[174:177], v[62:65]
	v_mfma_f32_16x16x32_bf16 v[58:61], v[74:77], v[174:177], v[58:61]
	v_mfma_f32_16x16x32_bf16 v[54:57], v[66:69], v[182:185], v[54:57]
	v_mfma_f32_16x16x32_bf16 v[50:53], v[74:77], v[182:185], v[50:53]
	v_mfma_f32_16x16x32_bf16 v[30:33], v[66:69], v[190:193], v[30:33]
	v_mfma_f32_16x16x32_bf16 v[26:29], v[74:77], v[190:193], v[26:29]
	v_mfma_f32_16x16x32_bf16 v[22:25], v[66:69], v[198:201], v[22:25]
	v_mfma_f32_16x16x32_bf16 v[10:13], v[74:77], v[198:201], v[10:13]
	v_mfma_f32_16x16x32_bf16 v[62:65], v[70:73], v[178:181], v[62:65]
	v_mfma_f32_16x16x32_bf16 v[58:61], v[102:105], v[178:181], v[58:61]
	v_mfma_f32_16x16x32_bf16 v[54:57], v[70:73], v[186:189], v[54:57]
	v_mfma_f32_16x16x32_bf16 v[50:53], v[102:105], v[186:189], v[50:53]
	v_mfma_f32_16x16x32_bf16 v[30:33], v[70:73], v[194:197], v[30:33]
	v_mfma_f32_16x16x32_bf16 v[26:29], v[102:105], v[194:197], v[26:29]
	v_mfma_f32_16x16x32_bf16 v[22:25], v[70:73], v[202:205], v[22:25]
	v_mfma_f32_16x16x32_bf16 v[10:13], v[102:105], v[202:205], v[10:13]
	v_mfma_f32_16x16x32_bf16 v[46:49], v[152:155], v[174:177], v[46:49]
	v_mfma_f32_16x16x32_bf16 v[42:45], v[166:169], v[174:177], v[42:45]
	v_mfma_f32_16x16x32_bf16 v[38:41], v[152:155], v[182:185], v[38:41]
	v_mfma_f32_16x16x32_bf16 v[34:37], v[166:169], v[182:185], v[34:37]
	v_mfma_f32_16x16x32_bf16 v[18:21], v[152:155], v[190:193], v[18:21]
	v_mfma_f32_16x16x32_bf16 v[14:17], v[166:169], v[190:193], v[14:17]
	v_mfma_f32_16x16x32_bf16 v[6:9], v[152:155], v[198:201], v[6:9]
	v_mfma_f32_16x16x32_bf16 v[2:5], v[166:169], v[198:201], v[2:5]
	v_mfma_f32_16x16x32_bf16 v[46:49], v[156:159], v[178:181], v[46:49]
	v_mfma_f32_16x16x32_bf16 v[42:45], v[170:173], v[178:181], v[42:45]
	v_mfma_f32_16x16x32_bf16 v[38:41], v[156:159], v[186:189], v[38:41]
	v_mfma_f32_16x16x32_bf16 v[34:37], v[170:173], v[186:189], v[34:37]
	v_mfma_f32_16x16x32_bf16 v[18:21], v[156:159], v[194:197], v[18:21]
	v_mfma_f32_16x16x32_bf16 v[14:17], v[170:173], v[194:197], v[14:17]
	v_mfma_f32_16x16x32_bf16 v[6:9], v[156:159], v[202:205], v[6:9]
	v_mfma_f32_16x16x32_bf16 v[2:5], v[170:173], v[202:205], v[2:5]
	s_setprio 0
	s_barrier
	s_add_i32 s34, 0, 0x18000
	s_add_i32 s35, 0, 0x1c000
	v_add_u32_e32 v102, s34, v162
	v_add_u32_e32 v165, s35, v162
	ds_read_b128 v[66:69], v102
	ds_read_b128 v[70:73], v102 offset:1024
	ds_read_b128 v[74:77], v102 offset:2048
	ds_read_b128 v[102:105], v102 offset:3072
	ds_read_b128 v[152:155], v165
	ds_read_b128 v[156:159], v165 offset:1024
	ds_read_b128 v[166:169], v165 offset:2048
	ds_read_b128 v[170:173], v165 offset:3072
	s_add_u32 s30, s56, 0x158000
	s_addc_u32 s31, s57, 0
	s_mov_b32 m0, s25
	v_lshl_add_u64 v[214:215], s[30:31], 0, v[0:1]
	ds_read_b128 v[174:177], v164 offset:32768
	ds_read_b128 v[178:181], v164 offset:33792
	ds_read_b128 v[182:185], v164 offset:34816
	ds_read_b128 v[186:189], v164 offset:35840
	ds_read_b128 v[190:193], v164 offset:36864
	ds_read_b128 v[194:197], v164 offset:37888
	ds_read_b128 v[198:201], v164 offset:38912
	ds_read_b128 v[202:205], v164 offset:39936
	global_load_lds_dwordx4 v[214:215], off
	s_mov_b32 m0, s66
	v_lshl_add_u64 v[214:215], s[30:31], 0, v[146:147]
	global_load_lds_dwordx4 v[214:215], off
	s_setprio 1
	s_waitcnt vmcnt(8) lgkmcnt(0)
	s_barrier
	v_mfma_f32_16x16x32_bf16 v[142:145], v[66:69], v[174:177], v[142:145]
	v_mfma_f32_16x16x32_bf16 v[138:141], v[74:77], v[174:177], v[138:141]
	v_mfma_f32_16x16x32_bf16 v[134:137], v[66:69], v[182:185], v[134:137]
	v_mfma_f32_16x16x32_bf16 v[130:133], v[74:77], v[182:185], v[130:133]
	v_mfma_f32_16x16x32_bf16 v[110:113], v[66:69], v[190:193], v[110:113]
	v_mfma_f32_16x16x32_bf16 v[106:109], v[74:77], v[190:193], v[106:109]
	v_mfma_f32_16x16x32_bf16 v[98:101], v[66:69], v[198:201], v[98:101]
	v_mfma_f32_16x16x32_bf16 v[94:97], v[74:77], v[198:201], v[94:97]
	v_mfma_f32_16x16x32_bf16 v[142:145], v[70:73], v[178:181], v[142:145]
	v_mfma_f32_16x16x32_bf16 v[138:141], v[102:105], v[178:181], v[138:141]
	v_mfma_f32_16x16x32_bf16 v[134:137], v[70:73], v[186:189], v[134:137]
	v_mfma_f32_16x16x32_bf16 v[130:133], v[102:105], v[186:189], v[130:133]
	v_mfma_f32_16x16x32_bf16 v[110:113], v[70:73], v[194:197], v[110:113]
	v_mfma_f32_16x16x32_bf16 v[106:109], v[102:105], v[194:197], v[106:109]
	v_mfma_f32_16x16x32_bf16 v[98:101], v[70:73], v[202:205], v[98:101]
	v_mfma_f32_16x16x32_bf16 v[94:97], v[102:105], v[202:205], v[94:97]
	v_mfma_f32_16x16x32_bf16 v[126:129], v[152:155], v[174:177], v[126:129]
	v_mfma_f32_16x16x32_bf16 v[122:125], v[166:169], v[174:177], v[122:125]
	v_mfma_f32_16x16x32_bf16 v[118:121], v[152:155], v[182:185], v[118:121]
	v_mfma_f32_16x16x32_bf16 v[114:117], v[166:169], v[182:185], v[114:117]
	v_mfma_f32_16x16x32_bf16 v[90:93], v[152:155], v[190:193], v[90:93]
	v_mfma_f32_16x16x32_bf16 v[86:89], v[166:169], v[190:193], v[86:89]
	v_mfma_f32_16x16x32_bf16 v[82:85], v[152:155], v[198:201], v[82:85]
	v_mfma_f32_16x16x32_bf16 v[78:81], v[166:169], v[198:201], v[78:81]
	v_mfma_f32_16x16x32_bf16 v[126:129], v[156:159], v[178:181], v[126:129]
	v_mfma_f32_16x16x32_bf16 v[122:125], v[170:173], v[178:181], v[122:125]
	v_mfma_f32_16x16x32_bf16 v[118:121], v[156:159], v[186:189], v[118:121]
	v_mfma_f32_16x16x32_bf16 v[114:117], v[170:173], v[186:189], v[114:117]
	v_mfma_f32_16x16x32_bf16 v[90:93], v[156:159], v[194:197], v[90:93]
	v_mfma_f32_16x16x32_bf16 v[86:89], v[170:173], v[194:197], v[86:89]
	v_mfma_f32_16x16x32_bf16 v[82:85], v[156:159], v[202:205], v[82:85]
	v_mfma_f32_16x16x32_bf16 v[78:81], v[170:173], v[202:205], v[78:81]
	s_setprio 0
	s_barrier
; #define PG8_STAGE(bufoff, gbase, voff) do { _Pragma("unroll") for (int _i = 0; _i < 2; ++_i) \
;         __builtin_amdgcn_global_load_lds((const unsigned*)((const char*)(gbase) + (voff)[_i]), (LAS unsigned*)(lds + (bufoff) + ldsw + _i * 8192), 16, 0, 0); } while (0)
; #define PG8_LDA(dst, b, h) do { _Pragma("unroll") for (int m = 0; m < 4; ++m) _Pragma("unroll") for (int k = 0; k < 2; ++k) dst[m][k] = *(const LAS bf16x8*)(lds + PG8_SA(b, h) + aoff + m * 2048 + k * 1024); } while (0)
; #define PG8_MMA(ai, bj, At, Bt) do { __builtin_amdgcn_s_setprio(1); _Pragma("unroll") for (int m = 0; m < 4; ++m) _Pragma("unroll") for (int n = 0; n < 2; ++n) _Pragma("unroll") for (int k = 0; k < 2; ++k) \
;         acc[ai][bj][m][n] = __builtin_amdgcn_mfma_f32_16x16x32_bf16(Bt[n][k], At[m][k], acc[ai][bj][m][n], 0, 0, 0); __builtin_amdgcn_s_setprio(0); } while (0)
; #define PG8_WAIT_V(n) asm volatile("s_waitcnt vmcnt(" #n ")" ::: "memory")
; #define PG8_WAIT_L(n) asm volatile("s_waitcnt lgkmcnt(" #n ")" ::: "memory")
; #define PG8_BAR __builtin_amdgcn_s_barrier()
; #define PG8_SCHED __builtin_amdgcn_sched_barrier(0)
; template <class Epi, int AMODE>
; __device__ __forceinline__ void gemm_phase(LAS unsigned char* lds, const Gemm g, const StaticOrder& S, const Epi& E, int stagger_us, int tid_in) {
;     ...
;             PG8_LDA(At, 1, 1); PG8_STAGE(PG8_SB(1, 0), b3, voffB); PG8_STAGE(PG8_SB(1, 1), b3 + hstepB, voffB); PG8_STAGE(PG8_SA(1, 0), a3, voffA);
;             PG8_WAIT_V(8); PG8_WAIT_L(0); PG8_BAR; PG8_MMA(1, 0, At, B0); PG8_MMA(1, 1, At, B1); PG8_BAR; PG8_SCHED;
	s_add_i32 s30, s34, s12
	v_lshl_add_u64 v[206:207], v[206:207], 0, s[74:75]
	s_mov_b32 m0, s30
	ds_read_b128 v[174:177], v164 offset:49152
	ds_read_b128 v[178:181], v164 offset:50176
	ds_read_b128 v[182:185], v164 offset:51200
	ds_read_b128 v[186:189], v164 offset:52224
	ds_read_b128 v[190:193], v164 offset:53248
	ds_read_b128 v[194:197], v164 offset:54272
	ds_read_b128 v[198:201], v164 offset:55296
	ds_read_b128 v[202:205], v164 offset:56320
	global_load_lds_dwordx4 v[206:207], off
	s_add_i32 m0, s30, 0x2000
	s_add_u32 s6, s6, 0x158080
	v_lshl_add_u64 v[206:207], v[208:209], 0, s[74:75]
	s_addc_u32 s7, s7, 0
	s_add_i32 s30, s35, s12
	global_load_lds_dwordx4 v[206:207], off
	s_mov_b32 m0, s30
	v_lshl_add_u64 v[206:207], s[6:7], 0, v[0:1]
	global_load_lds_dwordx4 v[206:207], off
	s_add_i32 m0, s30, 0x2000
	v_lshl_add_u64 v[206:207], s[6:7], 0, v[146:147]
	global_load_lds_dwordx4 v[206:207], off
	s_mov_b32 m0, s67
	v_lshl_add_u64 v[206:207], v[210:211], 0, s[74:75]
	global_load_lds_dwordx4 v[206:207], off
	s_mov_b32 m0, s69
	v_lshl_add_u64 v[206:207], v[212:213], 0, s[74:75]
	global_load_lds_dwordx4 v[206:207], off
	s_setprio 1
	s_waitcnt vmcnt(8) lgkmcnt(0)
	s_barrier
	v_mfma_f32_16x16x32_bf16 v[62:65], v[66:69], v[174:177], v[62:65]
	v_mfma_f32_16x16x32_bf16 v[58:61], v[74:77], v[174:177], v[58:61]
	v_mfma_f32_16x16x32_bf16 v[54:57], v[66:69], v[182:185], v[54:57]
	v_mfma_f32_16x16x32_bf16 v[50:53], v[74:77], v[182:185], v[50:53]
	v_mfma_f32_16x16x32_bf16 v[30:33], v[66:69], v[190:193], v[30:33]
	v_mfma_f32_16x16x32_bf16 v[26:29], v[74:77], v[190:193], v[26:29]
	v_mfma_f32_16x16x32_bf16 v[22:25], v[66:69], v[198:201], v[22:25]
	v_mfma_f32_16x16x32_bf16 v[10:13], v[74:77], v[198:201], v[10:13]
	v_mfma_f32_16x16x32_bf16 v[62:65], v[70:73], v[178:181], v[62:65]
	v_mfma_f32_16x16x32_bf16 v[58:61], v[102:105], v[178:181], v[58:61]
	v_mfma_f32_16x16x32_bf16 v[54:57], v[70:73], v[186:189], v[54:57]
	v_mfma_f32_16x16x32_bf16 v[50:53], v[102:105], v[186:189], v[50:53]
	v_mfma_f32_16x16x32_bf16 v[30:33], v[70:73], v[194:197], v[30:33]
	v_mfma_f32_16x16x32_bf16 v[26:29], v[102:105], v[194:197], v[26:29]
	v_mfma_f32_16x16x32_bf16 v[22:25], v[70:73], v[202:205], v[22:25]
	v_mfma_f32_16x16x32_bf16 v[10:13], v[102:105], v[202:205], v[10:13]
	v_mfma_f32_16x16x32_bf16 v[46:49], v[152:155], v[174:177], v[46:49]
	v_mfma_f32_16x16x32_bf16 v[42:45], v[166:169], v[174:177], v[42:45]
	v_mfma_f32_16x16x32_bf16 v[38:41], v[152:155], v[182:185], v[38:41]
	v_mfma_f32_16x16x32_bf16 v[34:37], v[166:169], v[182:185], v[34:37]
	v_mfma_f32_16x16x32_bf16 v[18:21], v[152:155], v[190:193], v[18:21]
	v_mfma_f32_16x16x32_bf16 v[14:17], v[166:169], v[190:193], v[14:17]
	v_mfma_f32_16x16x32_bf16 v[6:9], v[152:155], v[198:201], v[6:9]
	v_mfma_f32_16x16x32_bf16 v[2:5], v[166:169], v[198:201], v[2:5]
	v_mfma_f32_16x16x32_bf16 v[46:49], v[156:159], v[178:181], v[46:49]
	v_mfma_f32_16x16x32_bf16 v[42:45], v[170:173], v[178:181], v[42:45]
	v_mfma_f32_16x16x32_bf16 v[38:41], v[156:159], v[186:189], v[38:41]
	v_mfma_f32_16x16x32_bf16 v[34:37], v[170:173], v[186:189], v[34:37]
	v_mfma_f32_16x16x32_bf16 v[18:21], v[156:159], v[194:197], v[18:21]
	v_mfma_f32_16x16x32_bf16 v[14:17], v[170:173], v[194:197], v[14:17]
	v_mfma_f32_16x16x32_bf16 v[6:9], v[156:159], v[202:205], v[6:9]
	v_mfma_f32_16x16x32_bf16 v[2:5], v[170:173], v[202:205], v[2:5]
	s_setprio 0
	s_barrier
	s_add_i32 s29, s29, 2
	s_add_u32 s27, s27, 0x100
	s_addc_u32 s28, s28, 0
	s_cmpk_gt_u32 s29, 0x53
	s_mov_b64 s[54:55], s[4:5]
	s_cbranch_scc0 .LBB0_1476
	s_and_b64 vcc, exec, s[46:47]
	s_cbranch_vccz .LBB0_1479
	s_barrier

; #define PG8_STAGE(bufoff, gbase, voff) do { _Pragma("unroll") for (int _i = 0; _i < 2; ++_i) \
;         __builtin_amdgcn_global_load_lds((const unsigned*)((const char*)(gbase) + (voff)[_i]), (LAS unsigned*)(lds + (bufoff) + ldsw + _i * 8192), 16, 0, 0); } while (0)
; #define PG8_LDA(dst, b, h) do { _Pragma("unroll") for (int m = 0; m < 4; ++m) _Pragma("unroll") for (int k = 0; k < 2; ++k) dst[m][k] = *(const LAS bf16x8*)(lds + PG8_SA(b, h) + aoff + m * 2048 + k * 1024); } while (0)
; #define PG8_LDB(dst, b, h) do { _Pragma("unroll") for (int n = 0; n < 2; ++n) _Pragma("unroll") for (int k = 0; k < 2; ++k) dst[n][k] = *(const LAS bf16x8*)(lds + PG8_SB(b, h) + boff + n * 2048 + k * 1024); } while (0)
; #define PG8_MMA(ai, bj, At, Bt) do { __builtin_amdgcn_s_setprio(1); _Pragma("unroll") for (int m = 0; m < 4; ++m) _Pragma("unroll") for (int n = 0; n < 2; ++n) _Pragma("unroll") for (int k = 0; k < 2; ++k) \
;         acc[ai][bj][m][n] = __builtin_amdgcn_mfma_f32_16x16x32_bf16(Bt[n][k], At[m][k], acc[ai][bj][m][n], 0, 0, 0); __builtin_amdgcn_s_setprio(0); } while (0)
; #define PG8_WAIT_V(n) asm volatile("s_waitcnt vmcnt(" #n ")" ::: "memory")
; #define PG8_WAIT_L(n) asm volatile("s_waitcnt lgkmcnt(" #n ")" ::: "memory")
; #define PG8_BAR __builtin_amdgcn_s_barrier()
; template <class Epi, int AMODE>
; __device__ __forceinline__ void gemm_phase(LAS unsigned char* lds, const Gemm g, const StaticOrder& S, const Epi& E, int stagger_us, int tid_in) {
;     ...
;         const char* nA = has_next ? Abase + (size_t)nxt.pm * tstepA : cA; const char* nB = has_next ? (const char*)g.Bt + (size_t)nxt.pn * tstepB : cB;
;         for (int t = 0; t < nt; t += 2) {
;             const bool last = (t == nt - 2);
;             const char* a1 = cA + (size_t)(t + 1) * kstep;
;             const char* a2 = last ? nA : cA + (size_t)(t + 2) * kstep; const char* b2 = last ? nB : cB + (size_t)(t + 2) * kstep;
;             const char* a3 = a2 + kstep; const char* b3 = b2 + kstep;
;             PG8_LDB(B0, 0, 0); PG8_LDB(B1, 0, 1); PG8_SCHED; PG8_LDA(At, 0, 0); PG8_STAGE(PG8_SA(1, 1), a1 + hstepA, voffA);
;             PG8_WAIT_V(8); PG8_WAIT_L(0); PG8_BAR; PG8_MMA(0, 0, At, B0); PG8_MMA(0, 1, At, B1); PG8_BAR; PG8_SCHED;
;             PG8_LDA(At, 0, 1); PG8_STAGE(PG8_SB(0, 0), b2, voffB); PG8_STAGE(PG8_SB(0, 1), b2 + hstepB, voffB); PG8_STAGE(PG8_SA(0, 0), a2, voffA);
.LBB0_1498:
	s_add_u32 s4, s46, 0x100
	s_addc_u32 s5, s47, 0
	s_add_i32 s30, 0, 0x10000
	s_cmpk_eq_i32 s29, 0x52
	s_cselect_b32 s59, s41, s5
	s_cselect_b32 s58, s40, s4
	s_cselect_b32 s7, s57, s28
	s_cselect_b32 s6, s56, s27
	s_add_i32 s34, 0, 0x14000
	v_add_u32_e32 v62, s30, v209
	v_add_u32_e32 v158, s34, v209
	ds_read_b128 v[50:53], v62
	ds_read_b128 v[54:57], v62 offset:1024
	ds_read_b128 v[58:61], v62 offset:2048
	ds_read_b128 v[62:65], v62 offset:3072
	ds_read_b128 v[146:149], v158
	ds_read_b128 v[150:153], v158 offset:1024
	ds_read_b128 v[154:157], v158 offset:2048
	ds_read_b128 v[158:161], v158 offset:3072
	v_lshl_add_u64 v[200:201], s[46:47], 0, v[176:177]
	s_add_i32 m0, s13, 0xc000
	ds_read_b128 v[162:165], v215
	ds_read_b128 v[166:169], v215 offset:1024
	ds_read_b128 v[170:173], v215 offset:2048
	ds_read_b128 v[180:183], v215 offset:3072
	ds_read_b128 v[184:187], v215 offset:4096
	ds_read_b128 v[188:191], v215 offset:5120
	ds_read_b128 v[192:195], v215 offset:6144
	ds_read_b128 v[196:199], v215 offset:7168
	global_load_lds_dwordx4 v[200:201], off
	s_add_i32 m0, s13, 0xe000
	v_lshl_add_u64 v[200:201], s[46:47], 0, v[178:179]
	global_load_lds_dwordx4 v[200:201], off
	s_setprio 1
	s_waitcnt vmcnt(8) lgkmcnt(0)
	s_barrier
	v_mfma_f32_16x16x32_bf16 v[142:145], v[50:53], v[162:165], v[142:145]
	v_mfma_f32_16x16x32_bf16 v[138:141], v[58:61], v[162:165], v[138:141]
	v_mfma_f32_16x16x32_bf16 v[126:129], v[50:53], v[170:173], v[126:129]
	v_mfma_f32_16x16x32_bf16 v[122:125], v[58:61], v[170:173], v[122:125]
	v_mfma_f32_16x16x32_bf16 v[110:113], v[50:53], v[184:187], v[110:113]
	v_mfma_f32_16x16x32_bf16 v[106:109], v[58:61], v[184:187], v[106:109]
	v_mfma_f32_16x16x32_bf16 v[94:97], v[50:53], v[192:195], v[94:97]
	v_mfma_f32_16x16x32_bf16 v[90:93], v[58:61], v[192:195], v[90:93]
	v_mfma_f32_16x16x32_bf16 v[142:145], v[54:57], v[166:169], v[142:145]
	v_mfma_f32_16x16x32_bf16 v[138:141], v[62:65], v[166:169], v[138:141]
	v_mfma_f32_16x16x32_bf16 v[126:129], v[54:57], v[180:183], v[126:129]
	v_mfma_f32_16x16x32_bf16 v[122:125], v[62:65], v[180:183], v[122:125]
	v_mfma_f32_16x16x32_bf16 v[110:113], v[54:57], v[188:191], v[110:113]
	v_mfma_f32_16x16x32_bf16 v[106:109], v[62:65], v[188:191], v[106:109]
	v_mfma_f32_16x16x32_bf16 v[94:97], v[54:57], v[196:199], v[94:97]
	v_mfma_f32_16x16x32_bf16 v[90:93], v[62:65], v[196:199], v[90:93]
	v_mfma_f32_16x16x32_bf16 v[134:137], v[146:149], v[162:165], v[134:137]
	v_mfma_f32_16x16x32_bf16 v[130:133], v[154:157], v[162:165], v[130:133]
	v_mfma_f32_16x16x32_bf16 v[118:121], v[146:149], v[170:173], v[118:121]
	v_mfma_f32_16x16x32_bf16 v[114:117], v[154:157], v[170:173], v[114:117]
	v_mfma_f32_16x16x32_bf16 v[102:105], v[146:149], v[184:187], v[102:105]
	v_mfma_f32_16x16x32_bf16 v[98:101], v[154:157], v[184:187], v[98:101]
	v_mfma_f32_16x16x32_bf16 v[86:89], v[146:149], v[192:195], v[86:89]
	v_mfma_f32_16x16x32_bf16 v[82:85], v[154:157], v[192:195], v[82:85]
	v_mfma_f32_16x16x32_bf16 v[134:137], v[150:153], v[166:169], v[134:137]
	v_mfma_f32_16x16x32_bf16 v[130:133], v[158:161], v[166:169], v[130:133]
	v_mfma_f32_16x16x32_bf16 v[118:121], v[150:153], v[180:183], v[118:121]
	v_mfma_f32_16x16x32_bf16 v[114:117], v[158:161], v[180:183], v[114:117]
	v_mfma_f32_16x16x32_bf16 v[102:105], v[150:153], v[188:191], v[102:105]
	v_mfma_f32_16x16x32_bf16 v[98:101], v[158:161], v[188:191], v[98:101]
	v_mfma_f32_16x16x32_bf16 v[86:89], v[150:153], v[196:199], v[86:89]
	v_mfma_f32_16x16x32_bf16 v[82:85], v[158:161], v[196:199], v[82:85]
	s_setprio 0
	s_barrier
	s_add_i32 s30, s30, s12
	v_lshl_add_u64 v[200:201], s[6:7], 0, v[0:1]
	s_mov_b32 m0, s30
	ds_read_b128 v[162:165], v215 offset:16384
	ds_read_b128 v[166:169], v215 offset:17408
	ds_read_b128 v[170:173], v215 offset:18432
	ds_read_b128 v[180:183], v215 offset:19456
	ds_read_b128 v[184:187], v215 offset:20480
	ds_read_b128 v[188:191], v215 offset:21504
	ds_read_b128 v[192:195], v215 offset:22528
	ds_read_b128 v[196:199], v215 offset:23552
	global_load_lds_dwordx4 v[200:201], off
	s_add_i32 m0, s30, 0x2000
	s_add_u32 s30, s6, 0x158000
	v_lshl_add_u64 v[202:203], s[6:7], 0, v[174:175]
	s_addc_u32 s31, s7, 0
	s_add_i32 s34, s34, s12
	global_load_lds_dwordx4 v[202:203], off
	v_lshl_add_u64 v[204:205], s[30:31], 0, v[0:1]
	s_mov_b32 m0, s34
	v_lshl_add_u64 v[206:207], s[58:59], 0, v[174:175]
	global_load_lds_dwordx4 v[204:205], off
	s_add_i32 m0, s34, 0x2000
	v_lshl_add_u64 v[204:205], s[30:31], 0, v[174:175]
	global_load_lds_dwordx4 v[204:205], off
	s_mov_b32 m0, s13
	v_lshl_add_u64 v[204:205], s[58:59], 0, v[0:1]
	global_load_lds_dwordx4 v[204:205], off
	s_mov_b32 m0, s24
	s_nop 0
	global_load_lds_dwordx4 v[206:207], off
	s_setprio 1
	s_waitcnt vmcnt(8) lgkmcnt(0)
	s_barrier
; #define PG8_STAGE(bufoff, gbase, voff) do { _Pragma("unroll") for (int _i = 0; _i < 2; ++_i) \
;         __builtin_amdgcn_global_load_lds((const unsigned*)((const char*)(gbase) + (voff)[_i]), (LAS unsigned*)(lds + (bufoff) + ldsw + _i * 8192), 16, 0, 0); } while (0)
; #define PG8_LDA(dst, b, h) do { _Pragma("unroll") for (int m = 0; m < 4; ++m) _Pragma("unroll") for (int k = 0; k < 2; ++k) dst[m][k] = *(const LAS bf16x8*)(lds + PG8_SA(b, h) + aoff + m * 2048 + k * 1024); } while (0)
; #define PG8_LDB(dst, b, h) do { _Pragma("unroll") for (int n = 0; n < 2; ++n) _Pragma("unroll") for (int k = 0; k < 2; ++k) dst[n][k] = *(const LAS bf16x8*)(lds + PG8_SB(b, h) + boff + n * 2048 + k * 1024); } while (0)
; #define PG8_MMA(ai, bj, At, Bt) do { __builtin_amdgcn_s_setprio(1); _Pragma("unroll") for (int m = 0; m < 4; ++m) _Pragma("unroll") for (int n = 0; n < 2; ++n) _Pragma("unroll") for (int k = 0; k < 2; ++k) \
;         acc[ai][bj][m][n] = __builtin_amdgcn_mfma_f32_16x16x32_bf16(Bt[n][k], At[m][k], acc[ai][bj][m][n], 0, 0, 0); __builtin_amdgcn_s_setprio(0); } while (0)
; #define PG8_WAIT_V(n) asm volatile("s_waitcnt vmcnt(" #n ")" ::: "memory")
; #define PG8_WAIT_L(n) asm volatile("s_waitcnt lgkmcnt(" #n ")" ::: "memory")
; #define PG8_BAR __builtin_amdgcn_s_barrier()
; #define PG8_SCHED __builtin_amdgcn_sched_barrier(0)
; template <class Epi, int AMODE>
; __device__ __forceinline__ void gemm_phase(LAS unsigned char* lds, const Gemm g, const StaticOrder& S, const Epi& E, int stagger_us, int tid_in) {
;     ...
;             PG8_WAIT_V(8); PG8_WAIT_L(0); PG8_BAR; PG8_MMA(1, 0, At, B0); PG8_MMA(1, 1, At, B1); PG8_BAR; PG8_SCHED;
;             PG8_LDB(B0, 1, 0); PG8_LDB(B1, 1, 1); PG8_SCHED; PG8_LDA(At, 1, 0); PG8_STAGE(PG8_SA(0, 1), a2 + hstepA, voffA);
;             PG8_WAIT_V(8); PG8_WAIT_L(0); PG8_BAR; PG8_MMA(0, 0, At, B0); PG8_MMA(0, 1, At, B1); PG8_BAR; PG8_SCHED;
	v_mfma_f32_16x16x32_bf16 v[78:81], v[50:53], v[162:165], v[78:81]
	v_mfma_f32_16x16x32_bf16 v[74:77], v[58:61], v[162:165], v[74:77]
	v_mfma_f32_16x16x32_bf16 v[46:49], v[50:53], v[170:173], v[46:49]
	v_mfma_f32_16x16x32_bf16 v[42:45], v[58:61], v[170:173], v[42:45]
	v_mfma_f32_16x16x32_bf16 v[30:33], v[50:53], v[184:187], v[30:33]
	v_mfma_f32_16x16x32_bf16 v[26:29], v[58:61], v[184:187], v[26:29]
	v_mfma_f32_16x16x32_bf16 v[14:17], v[50:53], v[192:195], v[14:17]
	v_mfma_f32_16x16x32_bf16 v[10:13], v[58:61], v[192:195], v[10:13]
	v_mfma_f32_16x16x32_bf16 v[78:81], v[54:57], v[166:169], v[78:81]
	v_mfma_f32_16x16x32_bf16 v[74:77], v[62:65], v[166:169], v[74:77]
	v_mfma_f32_16x16x32_bf16 v[46:49], v[54:57], v[180:183], v[46:49]
	v_mfma_f32_16x16x32_bf16 v[42:45], v[62:65], v[180:183], v[42:45]
	v_mfma_f32_16x16x32_bf16 v[30:33], v[54:57], v[188:191], v[30:33]
	v_mfma_f32_16x16x32_bf16 v[26:29], v[62:65], v[188:191], v[26:29]
	v_mfma_f32_16x16x32_bf16 v[14:17], v[54:57], v[196:199], v[14:17]
	v_mfma_f32_16x16x32_bf16 v[10:13], v[62:65], v[196:199], v[10:13]
	v_mfma_f32_16x16x32_bf16 v[38:41], v[146:149], v[170:173], v[38:41]
	v_mfma_f32_16x16x32_bf16 v[34:37], v[154:157], v[170:173], v[34:37]
	v_mfma_f32_16x16x32_bf16 v[22:25], v[146:149], v[184:187], v[22:25]
	v_mfma_f32_16x16x32_bf16 v[18:21], v[154:157], v[184:187], v[18:21]
	v_mfma_f32_16x16x32_bf16 v[6:9], v[146:149], v[192:195], v[6:9]
	v_mfma_f32_16x16x32_bf16 v[2:5], v[154:157], v[192:195], v[2:5]
	v_mfma_f32_16x16x32_bf16 v[50:53], v[146:149], v[162:165], v[70:73]
	v_mfma_f32_16x16x32_bf16 v[54:57], v[154:157], v[162:165], v[66:69]
	v_mfma_f32_16x16x32_bf16 v[38:41], v[150:153], v[180:183], v[38:41]
	v_mfma_f32_16x16x32_bf16 v[34:37], v[158:161], v[180:183], v[34:37]
	v_mfma_f32_16x16x32_bf16 v[22:25], v[150:153], v[188:191], v[22:25]
	v_mfma_f32_16x16x32_bf16 v[18:21], v[158:161], v[188:191], v[18:21]
	v_mfma_f32_16x16x32_bf16 v[6:9], v[150:153], v[196:199], v[6:9]
	v_mfma_f32_16x16x32_bf16 v[2:5], v[158:161], v[196:199], v[2:5]
	v_mfma_f32_16x16x32_bf16 v[50:53], v[150:153], v[166:169], v[50:53]
	v_mfma_f32_16x16x32_bf16 v[54:57], v[158:161], v[166:169], v[54:57]
	s_setprio 0
	s_barrier
	s_add_i32 s34, 0, 0x18000
	s_add_i32 s35, 0, 0x1c000
	v_add_u32_e32 v70, s34, v209
	v_add_u32_e32 v158, s35, v209
	ds_read_b128 v[58:61], v70
	ds_read_b128 v[62:65], v70 offset:1024
	ds_read_b128 v[66:69], v70 offset:2048
	ds_read_b128 v[70:73], v70 offset:3072
	ds_read_b128 v[146:149], v158
	ds_read_b128 v[150:153], v158 offset:1024
	ds_read_b128 v[154:157], v158 offset:2048
	ds_read_b128 v[158:161], v158 offset:3072
	s_add_u32 s30, s58, 0x158000
	s_addc_u32 s31, s59, 0
	s_mov_b32 m0, s25
	v_lshl_add_u64 v[210:211], s[30:31], 0, v[0:1]
	ds_read_b128 v[162:165], v215 offset:32768
	ds_read_b128 v[166:169], v215 offset:33792
	ds_read_b128 v[170:173], v215 offset:34816
	ds_read_b128 v[180:183], v215 offset:35840
	ds_read_b128 v[184:187], v215 offset:36864
	ds_read_b128 v[188:191], v215 offset:37888
	ds_read_b128 v[192:195], v215 offset:38912
	ds_read_b128 v[196:199], v215 offset:39936
	global_load_lds_dwordx4 v[210:211], off
	s_mov_b32 m0, s66
	v_lshl_add_u64 v[210:211], s[30:31], 0, v[174:175]
	global_load_lds_dwordx4 v[210:211], off
	s_setprio 1
	s_waitcnt vmcnt(8) lgkmcnt(0)
	s_barrier
	v_mfma_f32_16x16x32_bf16 v[142:145], v[58:61], v[162:165], v[142:145]
	v_mfma_f32_16x16x32_bf16 v[138:141], v[66:69], v[162:165], v[138:141]
	v_mfma_f32_16x16x32_bf16 v[126:129], v[58:61], v[170:173], v[126:129]
	v_mfma_f32_16x16x32_bf16 v[122:125], v[66:69], v[170:173], v[122:125]
	v_mfma_f32_16x16x32_bf16 v[110:113], v[58:61], v[184:187], v[110:113]
	v_mfma_f32_16x16x32_bf16 v[106:109], v[66:69], v[184:187], v[106:109]
	v_mfma_f32_16x16x32_bf16 v[94:97], v[58:61], v[192:195], v[94:97]
	v_mfma_f32_16x16x32_bf16 v[90:93], v[66:69], v[192:195], v[90:93]
	v_mfma_f32_16x16x32_bf16 v[142:145], v[62:65], v[166:169], v[142:145]
	v_mfma_f32_16x16x32_bf16 v[138:141], v[70:73], v[166:169], v[138:141]
	v_mfma_f32_16x16x32_bf16 v[126:129], v[62:65], v[180:183], v[126:129]
	v_mfma_f32_16x16x32_bf16 v[122:125], v[70:73], v[180:183], v[122:125]
	v_mfma_f32_16x16x32_bf16 v[110:113], v[62:65], v[188:191], v[110:113]
	v_mfma_f32_16x16x32_bf16 v[106:109], v[70:73], v[188:191], v[106:109]
	v_mfma_f32_16x16x32_bf16 v[94:97], v[62:65], v[196:199], v[94:97]
	v_mfma_f32_16x16x32_bf16 v[90:93], v[70:73], v[196:199], v[90:93]
	v_mfma_f32_16x16x32_bf16 v[134:137], v[146:149], v[162:165], v[134:137]
	v_mfma_f32_16x16x32_bf16 v[130:133], v[154:157], v[162:165], v[130:133]
	v_mfma_f32_16x16x32_bf16 v[118:121], v[146:149], v[170:173], v[118:121]
	v_mfma_f32_16x16x32_bf16 v[114:117], v[154:157], v[170:173], v[114:117]
	v_mfma_f32_16x16x32_bf16 v[102:105], v[146:149], v[184:187], v[102:105]
	v_mfma_f32_16x16x32_bf16 v[98:101], v[154:157], v[184:187], v[98:101]
	v_mfma_f32_16x16x32_bf16 v[86:89], v[146:149], v[192:195], v[86:89]
	v_mfma_f32_16x16x32_bf16 v[82:85], v[154:157], v[192:195], v[82:85]
	v_mfma_f32_16x16x32_bf16 v[134:137], v[150:153], v[166:169], v[134:137]
	v_mfma_f32_16x16x32_bf16 v[130:133], v[158:161], v[166:169], v[130:133]
	v_mfma_f32_16x16x32_bf16 v[118:121], v[150:153], v[180:183], v[118:121]
	v_mfma_f32_16x16x32_bf16 v[114:117], v[158:161], v[180:183], v[114:117]
	v_mfma_f32_16x16x32_bf16 v[102:105], v[150:153], v[188:191], v[102:105]
	v_mfma_f32_16x16x32_bf16 v[98:101], v[158:161], v[188:191], v[98:101]
	v_mfma_f32_16x16x32_bf16 v[86:89], v[150:153], v[196:199], v[86:89]
	v_mfma_f32_16x16x32_bf16 v[82:85], v[158:161], v[196:199], v[82:85]
	s_setprio 0
	s_barrier
; #define PG8_STAGE(bufoff, gbase, voff) do { _Pragma("unroll") for (int _i = 0; _i < 2; ++_i) \
;         __builtin_amdgcn_global_load_lds((const unsigned*)((const char*)(gbase) + (voff)[_i]), (LAS unsigned*)(lds + (bufoff) + ldsw + _i * 8192), 16, 0, 0); } while (0)
; #define PG8_LDA(dst, b, h) do { _Pragma("unroll") for (int m = 0; m < 4; ++m) _Pragma("unroll") for (int k = 0; k < 2; ++k) dst[m][k] = *(const LAS bf16x8*)(lds + PG8_SA(b, h) + aoff + m * 2048 + k * 1024); } while (0)
; #define PG8_MMA(ai, bj, At, Bt) do { __builtin_amdgcn_s_setprio(1); _Pragma("unroll") for (int m = 0; m < 4; ++m) _Pragma("unroll") for (int n = 0; n < 2; ++n) _Pragma("unroll") for (int k = 0; k < 2; ++k) \
;         acc[ai][bj][m][n] = __builtin_amdgcn_mfma_f32_16x16x32_bf16(Bt[n][k], At[m][k], acc[ai][bj][m][n], 0, 0, 0); __builtin_amdgcn_s_setprio(0); } while (0)
; #define PG8_WAIT_V(n) asm volatile("s_waitcnt vmcnt(" #n ")" ::: "memory")
; #define PG8_WAIT_L(n) asm volatile("s_waitcnt lgkmcnt(" #n ")" ::: "memory")
; #define PG8_BAR __builtin_amdgcn_s_barrier()
; #define PG8_SCHED __builtin_amdgcn_sched_barrier(0)
; template <class Epi, int AMODE>
; __device__ __forceinline__ void gemm_phase(LAS unsigned char* lds, const Gemm g, const StaticOrder& S, const Epi& E, int stagger_us, int tid_in) {
;     ...
;             PG8_LDA(At, 1, 1); PG8_STAGE(PG8_SB(1, 0), b3, voffB); PG8_STAGE(PG8_SB(1, 1), b3 + hstepB, voffB); PG8_STAGE(PG8_SA(1, 0), a3, voffA);
;             PG8_WAIT_V(8); PG8_WAIT_L(0); PG8_BAR; PG8_MMA(1, 0, At, B0); PG8_MMA(1, 1, At, B1); PG8_BAR; PG8_SCHED;
	s_add_i32 s30, s34, s12
	v_lshl_add_u64 v[200:201], v[200:201], 0, s[74:75]
	s_mov_b32 m0, s30
	ds_read_b128 v[162:165], v215 offset:49152
	ds_read_b128 v[166:169], v215 offset:50176
	ds_read_b128 v[170:173], v215 offset:51200
	ds_read_b128 v[180:183], v215 offset:52224
	ds_read_b128 v[184:187], v215 offset:53248
	ds_read_b128 v[188:191], v215 offset:54272
	ds_read_b128 v[192:195], v215 offset:55296
	ds_read_b128 v[196:199], v215 offset:56320
	global_load_lds_dwordx4 v[200:201], off
	s_add_i32 m0, s30, 0x2000
	s_add_u32 s6, s6, 0x158080
	v_lshl_add_u64 v[200:201], v[202:203], 0, s[74:75]
	s_addc_u32 s7, s7, 0
	s_add_i32 s30, s35, s12
	global_load_lds_dwordx4 v[200:201], off
	s_mov_b32 m0, s30
	v_lshl_add_u64 v[200:201], s[6:7], 0, v[0:1]
	global_load_lds_dwordx4 v[200:201], off
	s_add_i32 m0, s30, 0x2000
	v_lshl_add_u64 v[200:201], s[6:7], 0, v[174:175]
	global_load_lds_dwordx4 v[200:201], off
	s_mov_b32 m0, s79
	v_lshl_add_u64 v[200:201], v[204:205], 0, s[74:75]
	global_load_lds_dwordx4 v[200:201], off
	s_mov_b32 m0, s83
	v_lshl_add_u64 v[200:201], v[206:207], 0, s[74:75]
	global_load_lds_dwordx4 v[200:201], off
	s_setprio 1
	s_waitcnt vmcnt(8) lgkmcnt(0)
	s_barrier
	v_mfma_f32_16x16x32_bf16 v[78:81], v[58:61], v[162:165], v[78:81]
	v_mfma_f32_16x16x32_bf16 v[74:77], v[66:69], v[162:165], v[74:77]
	v_mfma_f32_16x16x32_bf16 v[46:49], v[58:61], v[170:173], v[46:49]
	v_mfma_f32_16x16x32_bf16 v[42:45], v[66:69], v[170:173], v[42:45]
	v_mfma_f32_16x16x32_bf16 v[30:33], v[58:61], v[184:187], v[30:33]
	v_mfma_f32_16x16x32_bf16 v[26:29], v[66:69], v[184:187], v[26:29]
	v_mfma_f32_16x16x32_bf16 v[14:17], v[58:61], v[192:195], v[14:17]
	v_mfma_f32_16x16x32_bf16 v[10:13], v[66:69], v[192:195], v[10:13]
	v_mfma_f32_16x16x32_bf16 v[78:81], v[62:65], v[166:169], v[78:81]
	v_mfma_f32_16x16x32_bf16 v[74:77], v[70:73], v[166:169], v[74:77]
	v_mfma_f32_16x16x32_bf16 v[46:49], v[62:65], v[180:183], v[46:49]
	v_mfma_f32_16x16x32_bf16 v[42:45], v[70:73], v[180:183], v[42:45]
	v_mfma_f32_16x16x32_bf16 v[30:33], v[62:65], v[188:191], v[30:33]
	v_mfma_f32_16x16x32_bf16 v[26:29], v[70:73], v[188:191], v[26:29]
	v_mfma_f32_16x16x32_bf16 v[14:17], v[62:65], v[196:199], v[14:17]
	v_mfma_f32_16x16x32_bf16 v[10:13], v[70:73], v[196:199], v[10:13]
	v_mfma_f32_16x16x32_bf16 v[50:53], v[146:149], v[162:165], v[50:53]
	v_mfma_f32_16x16x32_bf16 v[70:73], v[150:153], v[166:169], v[50:53]
	v_mfma_f32_16x16x32_bf16 v[50:53], v[154:157], v[162:165], v[54:57]
	v_mfma_f32_16x16x32_bf16 v[38:41], v[146:149], v[170:173], v[38:41]
	v_mfma_f32_16x16x32_bf16 v[34:37], v[154:157], v[170:173], v[34:37]
	v_mfma_f32_16x16x32_bf16 v[22:25], v[146:149], v[184:187], v[22:25]
	v_mfma_f32_16x16x32_bf16 v[18:21], v[154:157], v[184:187], v[18:21]
	v_mfma_f32_16x16x32_bf16 v[6:9], v[146:149], v[192:195], v[6:9]
	v_mfma_f32_16x16x32_bf16 v[2:5], v[154:157], v[192:195], v[2:5]
	v_mfma_f32_16x16x32_bf16 v[66:69], v[158:161], v[166:169], v[50:53]
	v_mfma_f32_16x16x32_bf16 v[38:41], v[150:153], v[180:183], v[38:41]
	v_mfma_f32_16x16x32_bf16 v[34:37], v[158:161], v[180:183], v[34:37]
	v_mfma_f32_16x16x32_bf16 v[22:25], v[150:153], v[188:191], v[22:25]
	v_mfma_f32_16x16x32_bf16 v[18:21], v[158:161], v[188:191], v[18:21]
	v_mfma_f32_16x16x32_bf16 v[6:9], v[150:153], v[196:199], v[6:9]
	v_mfma_f32_16x16x32_bf16 v[2:5], v[158:161], v[196:199], v[2:5]
	s_setprio 0
	s_barrier
	s_add_i32 s29, s29, 2
	s_add_u32 s27, s27, 0x100
	s_addc_u32 s28, s28, 0
	s_cmpk_gt_u32 s29, 0x53
	s_mov_b64 s[46:47], s[4:5]
	s_cbranch_scc0 .LBB0_1498
	s_and_b64 vcc, exec, s[54:55]
	s_cbranch_vccz .LBB0_1501
	s_barrier
